# packed-f32 peepholes: FoX softmax s-m as v_pk_add_f32 (24 pairs per kv block) and xattn softmax scale*s-m as v_pk_fma_f32 (57 pairs), bit-identical math, fewer VALU issues
# baseline (speedup 1.0000x reference)
.LBB0_468:
	v_add_f32_e32 v171, 0xc2200000, v0
	s_add_i32 s18, s57, 0
	v_cmp_lt_f32_e32 vcc, v173, v171
	v_mov_b32_e32 v173, 0
	s_cmp_eq_u64 vcc, exec
	v_add3_u32 v169, s18, v159, v158
	s_cbranch_scc1 .LBB0_473
	v_pk_add_f32 v[84:85], v[84:85], v[0:1] op_sel_hi:[1,0] neg_lo:[0,1] neg_hi:[0,1]
	v_exp_f32_e32 v173, v84
	v_exp_f32_e32 v175, v85
	v_pk_add_f32 v[86:87], v[86:87], v[0:1] op_sel_hi:[1,0] neg_lo:[0,1] neg_hi:[0,1]
	v_exp_f32_e32 v179, v86
	v_exp_f32_e32 v181, v87
	v_pk_add_f32 v[88:89], v[88:89], v[0:1] op_sel_hi:[1,0] neg_lo:[0,1] neg_hi:[0,1]
	v_exp_f32_e32 v182, v88
	v_exp_f32_e32 v183, v89
	v_pk_add_f32 v[90:91], v[90:91], v[0:1] op_sel_hi:[1,0] neg_lo:[0,1] neg_hi:[0,1]
	v_exp_f32_e32 v184, v90
	v_exp_f32_e32 v185, v91
	v_pk_add_f32 v[92:93], v[92:93], v[0:1] op_sel_hi:[1,0] neg_lo:[0,1] neg_hi:[0,1]
	v_exp_f32_e32 v186, v92
	v_exp_f32_e32 v187, v93
	v_pk_add_f32 v[94:95], v[94:95], v[0:1] op_sel_hi:[1,0] neg_lo:[0,1] neg_hi:[0,1]
	v_exp_f32_e32 v188, v94
	v_exp_f32_e32 v189, v95
	ds_read_b64_tr_b16 v[84:85], v169 offset:36864
	ds_read_b64_tr_b16 v[86:87], v169 offset:38016
	v_sub_f32_e32 v88, v96, v0
	v_exp_f32_e32 v96, v88
	v_cvt_pk_bf16_f32 v88, v173, v175
	v_cvt_pk_bf16_f32 v89, v179, v181
	v_cvt_pk_bf16_f32 v90, v182, v183
	v_cvt_pk_bf16_f32 v91, v184, v185
	ds_read_b64_tr_b16 v[94:95], v169 offset:38080
	ds_read_b64_tr_b16 v[92:93], v169 offset:36928
	s_waitcnt lgkmcnt(2)
	v_mfma_f32_32x32x16_bf16 v[18:33], v[84:87], v[88:91], v[18:33]
	v_sub_f32_e32 v84, v97, v0
	v_exp_f32_e32 v97, v84
	v_sub_f32_e32 v84, v98, v0
	v_sub_f32_e32 v99, v99, v0
	v_exp_f32_e32 v98, v84
	ds_read_b64_tr_b16 v[84:85], v169 offset:39168
	ds_read_b64_tr_b16 v[86:87], v169 offset:40320
	v_exp_f32_e32 v99, v99
	s_waitcnt lgkmcnt(2)
	v_mfma_f32_32x32x16_bf16 v[2:17], v[92:95], v[88:91], v[2:17]
	v_cvt_pk_bf16_f32 v88, v186, v187
	v_cvt_pk_bf16_f32 v89, v188, v189
	v_cvt_pk_bf16_f32 v90, v96, v97
	v_cvt_pk_bf16_f32 v91, v98, v99
	ds_read_b64_tr_b16 v[94:95], v169 offset:40384
	ds_read_b64_tr_b16 v[92:93], v169 offset:39232
	s_waitcnt lgkmcnt(2)
	v_mfma_f32_32x32x16_bf16 v[18:33], v[84:87], v[88:91], v[18:33]
	v_add_f32_e32 v84, 0, v173
	v_add_f32_e32 v84, v175, v84
	v_add_f32_e32 v84, v179, v84
	v_add_f32_e32 v84, v181, v84
	v_add_f32_e32 v84, v182, v84
	v_add_f32_e32 v84, v183, v84
	v_add_f32_e32 v84, v184, v84
	v_add_f32_e32 v84, v185, v84
	s_waitcnt lgkmcnt(0)
	v_mfma_f32_32x32x16_bf16 v[2:17], v[92:95], v[88:91], v[2:17]
	v_add_f32_e32 v84, v186, v84
	v_add_f32_e32 v84, v187, v84
	v_add_f32_e32 v84, v188, v84
	v_add_f32_e32 v84, v189, v84
	v_add_f32_e32 v84, v96, v84
	v_add_f32_e32 v84, v97, v84
	v_add_f32_e32 v84, v98, v84
	v_add_f32_e32 v173, v99, v84
	v_cmp_lt_f32_e32 vcc, v174, v171
	s_cmp_eq_u64 vcc, exec
	s_cbranch_scc0 .LBB0_474

.LBB0_471:
	v_pk_add_f32 v[52:53], v[52:53], v[0:1] op_sel_hi:[1,0] neg_lo:[0,1] neg_hi:[0,1]
	v_exp_f32_e32 v68, v52
	v_exp_f32_e32 v69, v53
	v_pk_add_f32 v[54:55], v[54:55], v[0:1] op_sel_hi:[1,0] neg_lo:[0,1] neg_hi:[0,1]
	v_exp_f32_e32 v70, v54
	v_exp_f32_e32 v71, v55
	v_pk_add_f32 v[56:57], v[56:57], v[0:1] op_sel_hi:[1,0] neg_lo:[0,1] neg_hi:[0,1]
	v_exp_f32_e32 v72, v56
	v_exp_f32_e32 v73, v57
	v_pk_add_f32 v[58:59], v[58:59], v[0:1] op_sel_hi:[1,0] neg_lo:[0,1] neg_hi:[0,1]
	v_exp_f32_e32 v74, v58
	v_exp_f32_e32 v75, v59
	v_pk_add_f32 v[60:61], v[60:61], v[0:1] op_sel_hi:[1,0] neg_lo:[0,1] neg_hi:[0,1]
	v_exp_f32_e32 v76, v60
	v_exp_f32_e32 v77, v61
	v_pk_add_f32 v[62:63], v[62:63], v[0:1] op_sel_hi:[1,0] neg_lo:[0,1] neg_hi:[0,1]
	v_exp_f32_e32 v78, v62
	v_exp_f32_e32 v79, v63
	ds_read_b64_tr_b16 v[52:53], v169 offset:46080
	ds_read_b64_tr_b16 v[54:55], v169 offset:47232
	v_sub_f32_e32 v56, v64, v0
	v_exp_f32_e32 v64, v56
	v_cvt_pk_bf16_f32 v56, v68, v69
	v_cvt_pk_bf16_f32 v57, v70, v71
	v_cvt_pk_bf16_f32 v58, v72, v73
	v_cvt_pk_bf16_f32 v59, v74, v75
	ds_read_b64_tr_b16 v[62:63], v169 offset:47296
	ds_read_b64_tr_b16 v[60:61], v169 offset:46144
	s_waitcnt lgkmcnt(2)
	v_mfma_f32_32x32x16_bf16 v[18:33], v[52:55], v[56:59], v[18:33]
	v_sub_f32_e32 v52, v65, v0
	v_exp_f32_e32 v65, v52
	v_sub_f32_e32 v52, v66, v0
	v_sub_f32_e32 v67, v67, v0
	v_exp_f32_e32 v66, v52
	ds_read_b64_tr_b16 v[52:53], v169 offset:48384
	ds_read_b64_tr_b16 v[54:55], v169 offset:49536
	v_exp_f32_e32 v67, v67
	s_waitcnt lgkmcnt(2)
	v_mfma_f32_32x32x16_bf16 v[2:17], v[60:63], v[56:59], v[2:17]
	v_cvt_pk_bf16_f32 v56, v76, v77
	v_cvt_pk_bf16_f32 v57, v78, v79
	v_cvt_pk_bf16_f32 v58, v64, v65
	v_cvt_pk_bf16_f32 v59, v66, v67
	ds_read_b64_tr_b16 v[62:63], v169 offset:49600
	ds_read_b64_tr_b16 v[60:61], v169 offset:48448
	s_waitcnt lgkmcnt(2)
	v_mfma_f32_32x32x16_bf16 v[18:33], v[52:55], v[56:59], v[18:33]
	v_add_f32_e32 v52, v68, v173
	v_add_f32_e32 v52, v69, v52
	v_add_f32_e32 v52, v70, v52
	v_add_f32_e32 v52, v71, v52
	v_add_f32_e32 v52, v72, v52
	v_add_f32_e32 v52, v73, v52
	v_add_f32_e32 v52, v74, v52
	v_add_f32_e32 v52, v75, v52
	s_waitcnt lgkmcnt(0)
	v_mfma_f32_32x32x16_bf16 v[2:17], v[60:63], v[56:59], v[2:17]
	v_add_f32_e32 v52, v76, v52
	v_add_f32_e32 v52, v77, v52
	v_add_f32_e32 v52, v78, v52
	v_add_f32_e32 v52, v79, v52
	v_add_f32_e32 v52, v64, v52
	v_add_f32_e32 v52, v65, v52
	v_add_f32_e32 v52, v66, v52
	v_add_f32_e32 v173, v67, v52
	v_cmp_lt_f32_e32 vcc, v170, v171
	s_cmp_eq_u64 vcc, exec
	s_cbranch_scc0 .LBB0_476
	s_branch .LBB0_477

.LBB0_474:
	v_pk_add_f32 v[68:69], v[68:69], v[0:1] op_sel_hi:[1,0] neg_lo:[0,1] neg_hi:[0,1]
	v_exp_f32_e32 v84, v68
	v_exp_f32_e32 v85, v69
	v_pk_add_f32 v[70:71], v[70:71], v[0:1] op_sel_hi:[1,0] neg_lo:[0,1] neg_hi:[0,1]
	v_exp_f32_e32 v86, v70
	v_exp_f32_e32 v87, v71
	v_pk_add_f32 v[72:73], v[72:73], v[0:1] op_sel_hi:[1,0] neg_lo:[0,1] neg_hi:[0,1]
	v_exp_f32_e32 v88, v72
	v_exp_f32_e32 v89, v73
	v_pk_add_f32 v[74:75], v[74:75], v[0:1] op_sel_hi:[1,0] neg_lo:[0,1] neg_hi:[0,1]
	v_exp_f32_e32 v90, v74
	v_exp_f32_e32 v91, v75
	v_pk_add_f32 v[76:77], v[76:77], v[0:1] op_sel_hi:[1,0] neg_lo:[0,1] neg_hi:[0,1]
	v_exp_f32_e32 v92, v76
	v_exp_f32_e32 v93, v77
	v_pk_add_f32 v[78:79], v[78:79], v[0:1] op_sel_hi:[1,0] neg_lo:[0,1] neg_hi:[0,1]
	v_exp_f32_e32 v94, v78
	v_exp_f32_e32 v95, v79
	ds_read_b64_tr_b16 v[68:69], v169 offset:41472
	ds_read_b64_tr_b16 v[70:71], v169 offset:42624
	v_sub_f32_e32 v72, v80, v0
	v_exp_f32_e32 v80, v72
	v_cvt_pk_bf16_f32 v72, v84, v85
	v_cvt_pk_bf16_f32 v73, v86, v87
	v_cvt_pk_bf16_f32 v74, v88, v89
	v_cvt_pk_bf16_f32 v75, v90, v91
	ds_read_b64_tr_b16 v[78:79], v169 offset:42688
	ds_read_b64_tr_b16 v[76:77], v169 offset:41536
	s_waitcnt lgkmcnt(2)
	v_mfma_f32_32x32x16_bf16 v[18:33], v[68:71], v[72:75], v[18:33]
	v_sub_f32_e32 v68, v81, v0
	v_exp_f32_e32 v81, v68
	v_sub_f32_e32 v68, v82, v0
	v_sub_f32_e32 v83, v83, v0
	v_exp_f32_e32 v82, v68
	ds_read_b64_tr_b16 v[68:69], v169 offset:43776
	ds_read_b64_tr_b16 v[70:71], v169 offset:44928
	v_exp_f32_e32 v83, v83
	s_waitcnt lgkmcnt(2)
	v_mfma_f32_32x32x16_bf16 v[2:17], v[76:79], v[72:75], v[2:17]
	v_cvt_pk_bf16_f32 v72, v92, v93
	v_cvt_pk_bf16_f32 v73, v94, v95
	v_cvt_pk_bf16_f32 v74, v80, v81
	v_cvt_pk_bf16_f32 v75, v82, v83
	ds_read_b64_tr_b16 v[78:79], v169 offset:44992
	ds_read_b64_tr_b16 v[76:77], v169 offset:43840
	s_waitcnt lgkmcnt(2)
	v_mfma_f32_32x32x16_bf16 v[18:33], v[68:71], v[72:75], v[18:33]
	v_add_f32_e32 v68, v84, v173
	v_add_f32_e32 v68, v85, v68
	v_add_f32_e32 v68, v86, v68
	v_add_f32_e32 v68, v87, v68
	v_add_f32_e32 v68, v88, v68
	v_add_f32_e32 v68, v89, v68
	v_add_f32_e32 v68, v90, v68
	v_add_f32_e32 v68, v91, v68
	s_waitcnt lgkmcnt(0)
	v_mfma_f32_32x32x16_bf16 v[2:17], v[76:79], v[72:75], v[2:17]
	v_add_f32_e32 v68, v92, v68
	v_add_f32_e32 v68, v93, v68
	v_add_f32_e32 v68, v94, v68
	v_add_f32_e32 v68, v95, v68
	v_add_f32_e32 v68, v80, v68
	v_add_f32_e32 v68, v81, v68
	v_add_f32_e32 v68, v82, v68
	v_add_f32_e32 v173, v83, v68
	v_cmp_lt_f32_e32 vcc, v172, v171
	s_cmp_eq_u64 vcc, exec
	s_cbranch_scc0 .LBB0_471

.LBB0_476:
	v_pk_add_f32 v[36:37], v[36:37], v[0:1] op_sel_hi:[1,0] neg_lo:[0,1] neg_hi:[0,1]
	v_exp_f32_e32 v52, v36
	v_exp_f32_e32 v53, v37
	v_pk_add_f32 v[38:39], v[38:39], v[0:1] op_sel_hi:[1,0] neg_lo:[0,1] neg_hi:[0,1]
	v_exp_f32_e32 v54, v38
	v_exp_f32_e32 v55, v39
	v_pk_add_f32 v[40:41], v[40:41], v[0:1] op_sel_hi:[1,0] neg_lo:[0,1] neg_hi:[0,1]
	v_exp_f32_e32 v56, v40
	v_exp_f32_e32 v57, v41
	v_pk_add_f32 v[42:43], v[42:43], v[0:1] op_sel_hi:[1,0] neg_lo:[0,1] neg_hi:[0,1]
	v_exp_f32_e32 v58, v42
	v_exp_f32_e32 v59, v43
	v_pk_add_f32 v[44:45], v[44:45], v[0:1] op_sel_hi:[1,0] neg_lo:[0,1] neg_hi:[0,1]
	v_exp_f32_e32 v60, v44
	v_exp_f32_e32 v61, v45
	v_pk_add_f32 v[46:47], v[46:47], v[0:1] op_sel_hi:[1,0] neg_lo:[0,1] neg_hi:[0,1]
	v_exp_f32_e32 v62, v46
	v_exp_f32_e32 v63, v47
	ds_read_b64_tr_b16 v[36:37], v169 offset:50688
	ds_read_b64_tr_b16 v[38:39], v169 offset:51840
	v_sub_f32_e32 v40, v48, v0
	v_exp_f32_e32 v48, v40
	v_cvt_pk_bf16_f32 v40, v52, v53
	v_cvt_pk_bf16_f32 v41, v54, v55
	v_cvt_pk_bf16_f32 v42, v56, v57
	v_cvt_pk_bf16_f32 v43, v58, v59
	ds_read_b64_tr_b16 v[46:47], v169 offset:51904
	ds_read_b64_tr_b16 v[44:45], v169 offset:50752
	s_waitcnt lgkmcnt(2)
	v_mfma_f32_32x32x16_bf16 v[18:33], v[36:39], v[40:43], v[18:33]
	v_sub_f32_e32 v36, v49, v0
	v_exp_f32_e32 v49, v36
	v_sub_f32_e32 v36, v50, v0
	v_sub_f32_e32 v51, v51, v0
	v_exp_f32_e32 v50, v36
	ds_read_b64_tr_b16 v[36:37], v169 offset:52992
	ds_read_b64_tr_b16 v[38:39], v169 offset:54144
	v_exp_f32_e32 v51, v51
	s_waitcnt lgkmcnt(2)
	v_mfma_f32_32x32x16_bf16 v[2:17], v[44:47], v[40:43], v[2:17]
	v_cvt_pk_bf16_f32 v40, v60, v61
	v_cvt_pk_bf16_f32 v41, v62, v63
	v_cvt_pk_bf16_f32 v42, v48, v49
	v_cvt_pk_bf16_f32 v43, v50, v51
	ds_read_b64_tr_b16 v[46:47], v169 offset:54208
	ds_read_b64_tr_b16 v[44:45], v169 offset:53056
	s_waitcnt lgkmcnt(2)
	v_mfma_f32_32x32x16_bf16 v[18:33], v[36:39], v[40:43], v[18:33]
	v_add_f32_e32 v36, v52, v173
	v_add_f32_e32 v36, v53, v36
	v_add_f32_e32 v36, v54, v36
	v_add_f32_e32 v36, v55, v36
	v_add_f32_e32 v36, v56, v36
	v_add_f32_e32 v36, v57, v36
	v_add_f32_e32 v36, v58, v36
	v_add_f32_e32 v36, v59, v36
	s_waitcnt lgkmcnt(0)
	v_mfma_f32_32x32x16_bf16 v[2:17], v[44:47], v[40:43], v[2:17]
	v_add_f32_e32 v36, v60, v36
	v_add_f32_e32 v36, v61, v36
	v_add_f32_e32 v36, v62, v36
	v_add_f32_e32 v36, v63, v36
	v_add_f32_e32 v36, v48, v36
	v_add_f32_e32 v36, v49, v36
	v_add_f32_e32 v36, v50, v36
	v_add_f32_e32 v173, v51, v36

.LBB0_760:
	v_add_u32_e32 v181, 0x11800, v211
	v_add_u32_e32 v220, 0x15e00, v211
	v_add_u32_e32 v221, 0x1a400, v211
	v_add_u32_e32 v222, 0x1ea00, v211
	global_load_dwordx4 v[212:215], v[170:171], off offset:-128
	global_load_dwordx4 v[216:219], v[170:171], off offset:-96
	global_load_dwordx4 v[248:251], v[170:171], off offset:-64
	ds_read_b128 v[224:227], v211
	ds_read_b128 v[228:231], v211 offset:17920
	ds_read_b128 v[232:235], v211 offset:35840
	ds_read_b128 v[236:239], v211 offset:53760
	ds_read_b128 v[240:243], v181
	ds_read_b128 v[244:247], v220
	s_waitcnt vmcnt(2) lgkmcnt(5)
	v_mfma_f32_32x32x16_bf16 v[112:127], v[224:227], v[212:215], 0
	ds_read_b128 v[224:227], v221
	s_waitcnt lgkmcnt(5)
	v_mfma_f32_32x32x16_bf16 v[96:111], v[228:231], v[212:215], 0
	ds_read_b128 v[228:231], v222
	s_waitcnt lgkmcnt(5)
	v_mfma_f32_32x32x16_bf16 v[80:95], v[232:235], v[212:215], 0
	ds_read_b128 v[232:235], v211 offset:32
	s_waitcnt lgkmcnt(5)
	v_mfma_f32_32x32x16_bf16 v[64:79], v[236:239], v[212:215], 0
	ds_read_b128 v[236:239], v211 offset:17952
	s_waitcnt lgkmcnt(5)
	v_mfma_f32_32x32x16_bf16 v[48:63], v[240:243], v[212:215], 0
	ds_read_b128 v[240:243], v211 offset:35872
	s_waitcnt lgkmcnt(5)
	v_mfma_f32_32x32x16_bf16 v[32:47], v[244:247], v[212:215], 0
	ds_read_b128 v[244:247], v211 offset:53792
	s_waitcnt lgkmcnt(5)
	v_mfma_f32_32x32x16_bf16 v[16:31], v[224:227], v[212:215], 0
	ds_read_b128 v[224:227], v181 offset:32
	s_waitcnt lgkmcnt(5)
	v_mfma_f32_32x32x16_bf16 v[0:15], v[228:231], v[212:215], 0
	ds_read_b128 v[228:231], v220 offset:32
	global_load_dwordx4 v[212:215], v[170:171], off offset:-32
	s_waitcnt vmcnt(2) lgkmcnt(5)
	v_mfma_f32_32x32x16_bf16 v[112:127], v[232:235], v[216:219], v[112:127]
	ds_read_b128 v[232:235], v221 offset:32
	s_waitcnt lgkmcnt(5)
	v_mfma_f32_32x32x16_bf16 v[96:111], v[236:239], v[216:219], v[96:111]
	ds_read_b128 v[236:239], v222 offset:32
	s_waitcnt lgkmcnt(5)
	v_mfma_f32_32x32x16_bf16 v[80:95], v[240:243], v[216:219], v[80:95]
	ds_read_b128 v[240:243], v211 offset:64
	s_waitcnt lgkmcnt(5)
	v_mfma_f32_32x32x16_bf16 v[64:79], v[244:247], v[216:219], v[64:79]
	ds_read_b128 v[244:247], v211 offset:17984
	s_waitcnt lgkmcnt(5)
	v_mfma_f32_32x32x16_bf16 v[48:63], v[224:227], v[216:219], v[48:63]
	ds_read_b128 v[224:227], v211 offset:35904
	s_waitcnt lgkmcnt(5)
	v_mfma_f32_32x32x16_bf16 v[32:47], v[228:231], v[216:219], v[32:47]
	ds_read_b128 v[228:231], v211 offset:53824
	s_waitcnt lgkmcnt(5)
	v_mfma_f32_32x32x16_bf16 v[16:31], v[232:235], v[216:219], v[16:31]
	ds_read_b128 v[232:235], v181 offset:64
	s_waitcnt lgkmcnt(5)
	v_mfma_f32_32x32x16_bf16 v[0:15], v[236:239], v[216:219], v[0:15]
	ds_read_b128 v[236:239], v220 offset:64
	global_load_dwordx4 v[216:219], v[170:171], off
	s_waitcnt vmcnt(2) lgkmcnt(5)
	v_mfma_f32_32x32x16_bf16 v[112:127], v[240:243], v[248:251], v[112:127]
	ds_read_b128 v[240:243], v221 offset:64
	s_waitcnt lgkmcnt(5)
	v_mfma_f32_32x32x16_bf16 v[96:111], v[244:247], v[248:251], v[96:111]
	ds_read_b128 v[244:247], v222 offset:64
	s_waitcnt lgkmcnt(5)
	v_mfma_f32_32x32x16_bf16 v[80:95], v[224:227], v[248:251], v[80:95]
	ds_read_b128 v[224:227], v211 offset:96
	s_waitcnt lgkmcnt(5)
	v_mfma_f32_32x32x16_bf16 v[64:79], v[228:231], v[248:251], v[64:79]
	ds_read_b128 v[228:231], v211 offset:18016
	s_waitcnt lgkmcnt(5)
	v_mfma_f32_32x32x16_bf16 v[48:63], v[232:235], v[248:251], v[48:63]
	ds_read_b128 v[232:235], v211 offset:35936
	s_waitcnt lgkmcnt(5)
	v_mfma_f32_32x32x16_bf16 v[32:47], v[236:239], v[248:251], v[32:47]
	ds_read_b128 v[236:239], v211 offset:53856
	s_waitcnt lgkmcnt(5)
	v_mfma_f32_32x32x16_bf16 v[16:31], v[240:243], v[248:251], v[16:31]
	ds_read_b128 v[240:243], v181 offset:96
	s_waitcnt lgkmcnt(5)
	v_mfma_f32_32x32x16_bf16 v[0:15], v[244:247], v[248:251], v[0:15]
	ds_read_b128 v[244:247], v220 offset:96
	global_load_dwordx4 v[248:251], v[170:171], off offset:32
	s_waitcnt vmcnt(2) lgkmcnt(5)
	v_mfma_f32_32x32x16_bf16 v[112:127], v[224:227], v[212:215], v[112:127]
	ds_read_b128 v[224:227], v221 offset:96
	s_waitcnt lgkmcnt(5)
	v_mfma_f32_32x32x16_bf16 v[96:111], v[228:231], v[212:215], v[96:111]
	ds_read_b128 v[228:231], v222 offset:96
	s_waitcnt lgkmcnt(5)
	v_mfma_f32_32x32x16_bf16 v[80:95], v[232:235], v[212:215], v[80:95]
	ds_read_b128 v[232:235], v211 offset:128
	s_waitcnt lgkmcnt(5)
	v_mfma_f32_32x32x16_bf16 v[64:79], v[236:239], v[212:215], v[64:79]
	ds_read_b128 v[236:239], v211 offset:18048
	s_waitcnt lgkmcnt(5)
	v_mfma_f32_32x32x16_bf16 v[48:63], v[240:243], v[212:215], v[48:63]
	ds_read_b128 v[240:243], v211 offset:35968
	s_waitcnt lgkmcnt(5)
	v_mfma_f32_32x32x16_bf16 v[32:47], v[244:247], v[212:215], v[32:47]
	ds_read_b128 v[244:247], v211 offset:53888
	s_waitcnt lgkmcnt(5)
	v_mfma_f32_32x32x16_bf16 v[16:31], v[224:227], v[212:215], v[16:31]
	ds_read_b128 v[224:227], v181 offset:128
	s_waitcnt lgkmcnt(5)
	v_mfma_f32_32x32x16_bf16 v[0:15], v[228:231], v[212:215], v[0:15]
	ds_read_b128 v[228:231], v220 offset:128
	global_load_dwordx4 v[212:215], v[170:171], off offset:64
	s_waitcnt vmcnt(2) lgkmcnt(5)
	v_mfma_f32_32x32x16_bf16 v[112:127], v[232:235], v[216:219], v[112:127]
	ds_read_b128 v[232:235], v221 offset:128
	s_waitcnt lgkmcnt(5)
	v_mfma_f32_32x32x16_bf16 v[96:111], v[236:239], v[216:219], v[96:111]
	ds_read_b128 v[236:239], v222 offset:128
	s_waitcnt lgkmcnt(5)
	v_mfma_f32_32x32x16_bf16 v[80:95], v[240:243], v[216:219], v[80:95]
	ds_read_b128 v[240:243], v211 offset:160
	s_waitcnt lgkmcnt(5)
	v_mfma_f32_32x32x16_bf16 v[64:79], v[244:247], v[216:219], v[64:79]
	ds_read_b128 v[244:247], v211 offset:18080
	s_waitcnt lgkmcnt(5)
	v_mfma_f32_32x32x16_bf16 v[48:63], v[224:227], v[216:219], v[48:63]
	ds_read_b128 v[224:227], v211 offset:36000
	s_waitcnt lgkmcnt(5)
	v_mfma_f32_32x32x16_bf16 v[32:47], v[228:231], v[216:219], v[32:47]
	ds_read_b128 v[228:231], v211 offset:53920
	s_waitcnt lgkmcnt(5)
	v_mfma_f32_32x32x16_bf16 v[16:31], v[232:235], v[216:219], v[16:31]
	ds_read_b128 v[232:235], v181 offset:160
	s_waitcnt lgkmcnt(5)
	v_mfma_f32_32x32x16_bf16 v[0:15], v[236:239], v[216:219], v[0:15]
	ds_read_b128 v[236:239], v220 offset:160
	global_load_dwordx4 v[216:219], v[170:171], off offset:96
	s_waitcnt vmcnt(2) lgkmcnt(5)
	v_mfma_f32_32x32x16_bf16 v[112:127], v[240:243], v[248:251], v[112:127]
	ds_read_b128 v[240:243], v221 offset:160
	s_waitcnt lgkmcnt(5)
	v_mfma_f32_32x32x16_bf16 v[96:111], v[244:247], v[248:251], v[96:111]
	ds_read_b128 v[244:247], v222 offset:160
	s_waitcnt lgkmcnt(5)
	v_mfma_f32_32x32x16_bf16 v[80:95], v[224:227], v[248:251], v[80:95]
	ds_read_b128 v[224:227], v211 offset:192
	s_waitcnt lgkmcnt(5)
	v_mfma_f32_32x32x16_bf16 v[64:79], v[228:231], v[248:251], v[64:79]
	ds_read_b128 v[228:231], v211 offset:18112
	s_waitcnt lgkmcnt(5)
	v_mfma_f32_32x32x16_bf16 v[48:63], v[232:235], v[248:251], v[48:63]
	ds_read_b128 v[232:235], v211 offset:36032
	s_waitcnt lgkmcnt(5)
	v_mfma_f32_32x32x16_bf16 v[32:47], v[236:239], v[248:251], v[32:47]
	ds_read_b128 v[236:239], v211 offset:53952
	s_waitcnt lgkmcnt(5)
	v_mfma_f32_32x32x16_bf16 v[16:31], v[240:243], v[248:251], v[16:31]
	ds_read_b128 v[240:243], v181 offset:192
	s_waitcnt lgkmcnt(5)
	v_mfma_f32_32x32x16_bf16 v[0:15], v[244:247], v[248:251], v[0:15]
	ds_read_b128 v[244:247], v220 offset:192
	global_load_dwordx4 v[248:251], v[170:171], off offset:128
	s_waitcnt vmcnt(2) lgkmcnt(5)
	v_mfma_f32_32x32x16_bf16 v[112:127], v[224:227], v[212:215], v[112:127]
	ds_read_b128 v[224:227], v221 offset:192
	s_waitcnt lgkmcnt(5)
	v_mfma_f32_32x32x16_bf16 v[96:111], v[228:231], v[212:215], v[96:111]
	ds_read_b128 v[228:231], v222 offset:192
	s_waitcnt lgkmcnt(5)
	v_mfma_f32_32x32x16_bf16 v[80:95], v[232:235], v[212:215], v[80:95]
	ds_read_b128 v[232:235], v211 offset:224
	s_waitcnt lgkmcnt(5)
	v_mfma_f32_32x32x16_bf16 v[64:79], v[236:239], v[212:215], v[64:79]
	ds_read_b128 v[236:239], v211 offset:18144
	s_waitcnt lgkmcnt(5)
	v_mfma_f32_32x32x16_bf16 v[48:63], v[240:243], v[212:215], v[48:63]
	ds_read_b128 v[240:243], v211 offset:36064
	s_waitcnt lgkmcnt(5)
	v_mfma_f32_32x32x16_bf16 v[32:47], v[244:247], v[212:215], v[32:47]
	ds_read_b128 v[244:247], v211 offset:53984
	s_waitcnt lgkmcnt(5)
	v_mfma_f32_32x32x16_bf16 v[16:31], v[224:227], v[212:215], v[16:31]
	ds_read_b128 v[224:227], v181 offset:224
	s_waitcnt lgkmcnt(5)
	v_mfma_f32_32x32x16_bf16 v[0:15], v[228:231], v[212:215], v[0:15]
	ds_read_b128 v[228:231], v220 offset:224
	global_load_dwordx4 v[212:215], v[170:171], off offset:160
	s_waitcnt vmcnt(2) lgkmcnt(5)
	v_mfma_f32_32x32x16_bf16 v[112:127], v[232:235], v[216:219], v[112:127]
	ds_read_b128 v[232:235], v221 offset:224
	s_waitcnt lgkmcnt(5)
	v_mfma_f32_32x32x16_bf16 v[96:111], v[236:239], v[216:219], v[96:111]
	ds_read_b128 v[236:239], v222 offset:224
	s_waitcnt lgkmcnt(5)
	v_mfma_f32_32x32x16_bf16 v[80:95], v[240:243], v[216:219], v[80:95]
	ds_read_b128 v[240:243], v211 offset:256
	s_waitcnt lgkmcnt(5)
	v_mfma_f32_32x32x16_bf16 v[64:79], v[244:247], v[216:219], v[64:79]
	ds_read_b128 v[244:247], v211 offset:18176
	s_waitcnt lgkmcnt(5)
	v_mfma_f32_32x32x16_bf16 v[48:63], v[224:227], v[216:219], v[48:63]
	ds_read_b128 v[224:227], v211 offset:36096
	s_waitcnt lgkmcnt(5)
	v_mfma_f32_32x32x16_bf16 v[32:47], v[228:231], v[216:219], v[32:47]
	ds_read_b128 v[228:231], v211 offset:54016
	s_waitcnt lgkmcnt(5)
	v_mfma_f32_32x32x16_bf16 v[16:31], v[232:235], v[216:219], v[16:31]
	ds_read_b128 v[232:235], v181 offset:256
	s_waitcnt lgkmcnt(5)
	v_mfma_f32_32x32x16_bf16 v[0:15], v[236:239], v[216:219], v[0:15]
	ds_read_b128 v[236:239], v220 offset:256
	global_load_dwordx4 v[216:219], v[170:171], off offset:192
	s_waitcnt vmcnt(2) lgkmcnt(5)
	v_mfma_f32_32x32x16_bf16 v[112:127], v[240:243], v[248:251], v[112:127]
	ds_read_b128 v[240:243], v221 offset:256
	s_waitcnt lgkmcnt(5)
	v_mfma_f32_32x32x16_bf16 v[96:111], v[244:247], v[248:251], v[96:111]
	ds_read_b128 v[244:247], v222 offset:256
	s_waitcnt lgkmcnt(5)
	v_mfma_f32_32x32x16_bf16 v[80:95], v[224:227], v[248:251], v[80:95]
	ds_read_b128 v[224:227], v211 offset:288
	s_waitcnt lgkmcnt(5)
	v_mfma_f32_32x32x16_bf16 v[64:79], v[228:231], v[248:251], v[64:79]
	ds_read_b128 v[228:231], v211 offset:18208
	s_waitcnt lgkmcnt(5)
	v_mfma_f32_32x32x16_bf16 v[48:63], v[232:235], v[248:251], v[48:63]
	ds_read_b128 v[232:235], v211 offset:36128
	s_waitcnt lgkmcnt(5)
	v_mfma_f32_32x32x16_bf16 v[32:47], v[236:239], v[248:251], v[32:47]
	ds_read_b128 v[236:239], v211 offset:54048
	s_waitcnt lgkmcnt(5)
	v_mfma_f32_32x32x16_bf16 v[16:31], v[240:243], v[248:251], v[16:31]
	ds_read_b128 v[240:243], v181 offset:288
	s_waitcnt lgkmcnt(5)
	v_mfma_f32_32x32x16_bf16 v[0:15], v[244:247], v[248:251], v[0:15]
	ds_read_b128 v[244:247], v220 offset:288
	global_load_dwordx4 v[248:251], v[170:171], off offset:224
	s_waitcnt vmcnt(2) lgkmcnt(5)
	v_mfma_f32_32x32x16_bf16 v[112:127], v[224:227], v[212:215], v[112:127]
	ds_read_b128 v[224:227], v221 offset:288
	s_waitcnt lgkmcnt(5)
	v_mfma_f32_32x32x16_bf16 v[96:111], v[228:231], v[212:215], v[96:111]
	ds_read_b128 v[228:231], v222 offset:288
	s_waitcnt lgkmcnt(5)
	v_mfma_f32_32x32x16_bf16 v[80:95], v[232:235], v[212:215], v[80:95]
	ds_read_b128 v[232:235], v211 offset:320
	s_waitcnt lgkmcnt(5)
	v_mfma_f32_32x32x16_bf16 v[64:79], v[236:239], v[212:215], v[64:79]
	ds_read_b128 v[236:239], v211 offset:18240
	s_waitcnt lgkmcnt(5)
	v_mfma_f32_32x32x16_bf16 v[48:63], v[240:243], v[212:215], v[48:63]
	ds_read_b128 v[240:243], v211 offset:36160
	s_waitcnt lgkmcnt(5)
	v_mfma_f32_32x32x16_bf16 v[32:47], v[244:247], v[212:215], v[32:47]
	ds_read_b128 v[244:247], v211 offset:54080
	s_waitcnt lgkmcnt(5)
	v_mfma_f32_32x32x16_bf16 v[16:31], v[224:227], v[212:215], v[16:31]
	ds_read_b128 v[224:227], v181 offset:320
	s_waitcnt lgkmcnt(5)
	v_mfma_f32_32x32x16_bf16 v[0:15], v[228:231], v[212:215], v[0:15]
	ds_read_b128 v[228:231], v220 offset:320
	global_load_dwordx4 v[212:215], v[170:171], off offset:256
	s_waitcnt vmcnt(2) lgkmcnt(5)
	v_mfma_f32_32x32x16_bf16 v[112:127], v[232:235], v[216:219], v[112:127]
	ds_read_b128 v[232:235], v221 offset:320
	s_waitcnt lgkmcnt(5)
	v_mfma_f32_32x32x16_bf16 v[96:111], v[236:239], v[216:219], v[96:111]
	ds_read_b128 v[236:239], v222 offset:320
	s_waitcnt lgkmcnt(5)
	v_mfma_f32_32x32x16_bf16 v[80:95], v[240:243], v[216:219], v[80:95]
	ds_read_b128 v[240:243], v211 offset:352
	s_waitcnt lgkmcnt(5)
	v_mfma_f32_32x32x16_bf16 v[64:79], v[244:247], v[216:219], v[64:79]
	ds_read_b128 v[244:247], v211 offset:18272
	s_waitcnt lgkmcnt(5)
	v_mfma_f32_32x32x16_bf16 v[48:63], v[224:227], v[216:219], v[48:63]
	ds_read_b128 v[224:227], v211 offset:36192
	s_waitcnt lgkmcnt(5)
	v_mfma_f32_32x32x16_bf16 v[32:47], v[228:231], v[216:219], v[32:47]
	ds_read_b128 v[228:231], v211 offset:54112
	s_waitcnt lgkmcnt(5)
	v_mfma_f32_32x32x16_bf16 v[16:31], v[232:235], v[216:219], v[16:31]
	ds_read_b128 v[232:235], v181 offset:352
	s_waitcnt lgkmcnt(5)
	v_mfma_f32_32x32x16_bf16 v[0:15], v[236:239], v[216:219], v[0:15]
	ds_read_b128 v[236:239], v220 offset:352
	global_load_dwordx4 v[216:219], v[170:171], off offset:288
	s_waitcnt vmcnt(2) lgkmcnt(5)
	v_mfma_f32_32x32x16_bf16 v[112:127], v[240:243], v[248:251], v[112:127]
	ds_read_b128 v[240:243], v221 offset:352
	s_waitcnt lgkmcnt(5)
	v_mfma_f32_32x32x16_bf16 v[96:111], v[244:247], v[248:251], v[96:111]
	ds_read_b128 v[244:247], v222 offset:352
	s_waitcnt lgkmcnt(5)
	v_mfma_f32_32x32x16_bf16 v[80:95], v[224:227], v[248:251], v[80:95]
	ds_read_b128 v[224:227], v211 offset:384
	s_waitcnt lgkmcnt(5)
	v_mfma_f32_32x32x16_bf16 v[64:79], v[228:231], v[248:251], v[64:79]
	ds_read_b128 v[228:231], v211 offset:18304
	s_waitcnt lgkmcnt(5)
	v_mfma_f32_32x32x16_bf16 v[48:63], v[232:235], v[248:251], v[48:63]
	ds_read_b128 v[232:235], v211 offset:36224
	s_waitcnt lgkmcnt(5)
	v_mfma_f32_32x32x16_bf16 v[32:47], v[236:239], v[248:251], v[32:47]
	ds_read_b128 v[236:239], v211 offset:54144
	s_waitcnt lgkmcnt(5)
	v_mfma_f32_32x32x16_bf16 v[16:31], v[240:243], v[248:251], v[16:31]
	ds_read_b128 v[240:243], v181 offset:384
	s_waitcnt lgkmcnt(5)
	v_mfma_f32_32x32x16_bf16 v[0:15], v[244:247], v[248:251], v[0:15]
	ds_read_b128 v[244:247], v220 offset:384
	global_load_dwordx4 v[248:251], v[170:171], off offset:320
	s_waitcnt vmcnt(2) lgkmcnt(5)
	v_mfma_f32_32x32x16_bf16 v[112:127], v[224:227], v[212:215], v[112:127]
	ds_read_b128 v[224:227], v221 offset:384
	s_waitcnt lgkmcnt(5)
	v_mfma_f32_32x32x16_bf16 v[96:111], v[228:231], v[212:215], v[96:111]
	ds_read_b128 v[228:231], v222 offset:384
	s_waitcnt lgkmcnt(5)
	v_mfma_f32_32x32x16_bf16 v[80:95], v[232:235], v[212:215], v[80:95]
	ds_read_b128 v[232:235], v211 offset:416
	s_waitcnt lgkmcnt(5)
	v_mfma_f32_32x32x16_bf16 v[64:79], v[236:239], v[212:215], v[64:79]
	ds_read_b128 v[236:239], v211 offset:18336
	s_waitcnt lgkmcnt(5)
	v_mfma_f32_32x32x16_bf16 v[48:63], v[240:243], v[212:215], v[48:63]
	ds_read_b128 v[240:243], v211 offset:36256
	s_waitcnt lgkmcnt(5)
	v_mfma_f32_32x32x16_bf16 v[32:47], v[244:247], v[212:215], v[32:47]
	ds_read_b128 v[244:247], v211 offset:54176
	s_waitcnt lgkmcnt(5)
	v_mfma_f32_32x32x16_bf16 v[16:31], v[224:227], v[212:215], v[16:31]
	ds_read_b128 v[224:227], v181 offset:416
	s_waitcnt lgkmcnt(5)
	v_mfma_f32_32x32x16_bf16 v[0:15], v[228:231], v[212:215], v[0:15]
	ds_read_b128 v[228:231], v220 offset:416
	global_load_dwordx4 v[212:215], v[170:171], off offset:352
	s_waitcnt vmcnt(2) lgkmcnt(5)
	v_mfma_f32_32x32x16_bf16 v[112:127], v[232:235], v[216:219], v[112:127]
	ds_read_b128 v[232:235], v221 offset:416
	s_waitcnt lgkmcnt(5)
	v_mfma_f32_32x32x16_bf16 v[96:111], v[236:239], v[216:219], v[96:111]
	ds_read_b128 v[236:239], v222 offset:416
	s_waitcnt lgkmcnt(5)
	v_mfma_f32_32x32x16_bf16 v[80:95], v[240:243], v[216:219], v[80:95]
	ds_read_b128 v[240:243], v211 offset:448
	s_waitcnt lgkmcnt(5)
	v_mfma_f32_32x32x16_bf16 v[64:79], v[244:247], v[216:219], v[64:79]
	ds_read_b128 v[244:247], v211 offset:18368
	s_waitcnt lgkmcnt(5)
	v_mfma_f32_32x32x16_bf16 v[48:63], v[224:227], v[216:219], v[48:63]
	ds_read_b128 v[224:227], v211 offset:36288
	s_waitcnt lgkmcnt(5)
	v_mfma_f32_32x32x16_bf16 v[32:47], v[228:231], v[216:219], v[32:47]
	ds_read_b128 v[228:231], v211 offset:54208
	s_waitcnt lgkmcnt(5)
	v_mfma_f32_32x32x16_bf16 v[16:31], v[232:235], v[216:219], v[16:31]
	ds_read_b128 v[232:235], v181 offset:448
	s_waitcnt lgkmcnt(5)
	v_mfma_f32_32x32x16_bf16 v[0:15], v[236:239], v[216:219], v[0:15]
	ds_read_b128 v[236:239], v220 offset:448
	s_waitcnt vmcnt(1) lgkmcnt(5)
	v_mfma_f32_32x32x16_bf16 v[112:127], v[240:243], v[248:251], v[112:127]
	ds_read_b128 v[240:243], v221 offset:448
	s_waitcnt lgkmcnt(5)
	v_mfma_f32_32x32x16_bf16 v[96:111], v[244:247], v[248:251], v[96:111]
	ds_read_b128 v[244:247], v222 offset:448
	s_waitcnt lgkmcnt(5)
	v_mfma_f32_32x32x16_bf16 v[80:95], v[224:227], v[248:251], v[80:95]
	ds_read_b128 v[224:227], v211 offset:480
	s_waitcnt lgkmcnt(5)
	v_mfma_f32_32x32x16_bf16 v[64:79], v[228:231], v[248:251], v[64:79]
	ds_read_b128 v[228:231], v211 offset:18400
	s_waitcnt lgkmcnt(5)
	v_mfma_f32_32x32x16_bf16 v[48:63], v[232:235], v[248:251], v[48:63]
	ds_read_b128 v[232:235], v211 offset:36320
	s_waitcnt lgkmcnt(5)
	v_mfma_f32_32x32x16_bf16 v[32:47], v[236:239], v[248:251], v[32:47]
	ds_read_b128 v[236:239], v211 offset:54240
	s_waitcnt lgkmcnt(5)
	v_mfma_f32_32x32x16_bf16 v[16:31], v[240:243], v[248:251], v[16:31]
	ds_read_b128 v[240:243], v181 offset:480
	s_waitcnt lgkmcnt(5)
	v_mfma_f32_32x32x16_bf16 v[0:15], v[244:247], v[248:251], v[0:15]
	ds_read_b128 v[244:247], v220 offset:480
	s_waitcnt vmcnt(0) lgkmcnt(5)
	v_mfma_f32_32x32x16_bf16 v[112:127], v[224:227], v[212:215], v[112:127]
	ds_read_b128 v[224:227], v221 offset:480
	s_waitcnt lgkmcnt(5)
	v_mfma_f32_32x32x16_bf16 v[96:111], v[228:231], v[212:215], v[96:111]
	ds_read_b128 v[228:231], v222 offset:480
	s_waitcnt lgkmcnt(5)
	v_mfma_f32_32x32x16_bf16 v[80:95], v[232:235], v[212:215], v[80:95]
	s_waitcnt lgkmcnt(4)
	v_mfma_f32_32x32x16_bf16 v[64:79], v[236:239], v[212:215], v[64:79]
	s_waitcnt lgkmcnt(3)
	v_mfma_f32_32x32x16_bf16 v[48:63], v[240:243], v[212:215], v[48:63]
	s_waitcnt lgkmcnt(2)
	v_mfma_f32_32x32x16_bf16 v[32:47], v[244:247], v[212:215], v[32:47]
	s_waitcnt lgkmcnt(1)
	v_mfma_f32_32x32x16_bf16 v[16:31], v[224:227], v[212:215], v[16:31]
	s_waitcnt lgkmcnt(0)
	v_mfma_f32_32x32x16_bf16 v[0:15], v[228:231], v[212:215], v[0:15]
	s_movk_i32 s47, 0x200
	v_lshl_add_u64 v[244:245], v[160:161], 0, s[38:39]
	global_load_dwordx4 v[212:215], v[160:161], off offset:2432
	global_load_dwordx4 v[216:219], v[160:161], off offset:2304
	global_load_dwordx4 v[224:227], v[160:161], off offset:2176
	global_load_dwordx4 v[228:231], v[160:161], off offset:2048
	global_load_dwordx4 v[232:235], v[168:169], off offset:2048
	global_load_dwordx4 v[236:239], v[244:245], off offset:384
	global_load_dwordx4 v[240:243], v[244:245], off offset:256
	global_load_dwordx4 v[246:249], v[244:245], off offset:128
	v_mov_b32_e32 v170, v145
	v_mov_b32_e32 v171, v146
	v_mov_b32_e32 v145, v147
	v_mov_b32_e32 v146, v141
	v_mov_b32_e32 v147, v142
	v_mov_b32_e32 v141, v143
	v_pk_add_f32 v[144:145], v[170:171], v[144:145]
	v_pk_add_f32 v[140:141], v[146:147], v[140:141]
	v_pk_add_f32 v[144:145], v[144:145], v[144:145] op_sel:[0,1] op_sel_hi:[1,0]
	v_pk_add_f32 v[140:141], v[140:141], v[140:141] op_sel:[0,1] op_sel_hi:[1,0]
	v_add_f32_e32 v136, v136, v137
	v_add_f32_e32 v138, v138, v139
	v_mov_b32_e32 v145, v132
	v_mov_b32_e32 v141, v133
	v_mov_b32_e32 v137, v134
	v_mov_b32_e32 v139, v135
	v_pk_add_f32 v[132:133], v[144:145], v[140:141]
	v_pk_add_f32 v[134:135], v[136:137], v[138:139]
	s_lshl_b32 s10, s46, 1
	v_pk_add_f32 v[132:133], v[132:133], v[134:135]
	v_mov_b32_e32 v159, v149
	v_add_f32_e32 v132, v132, v133
	v_fmamk_f32 v132, v132, 0x3a800000, v180
	v_cmp_gt_f32_e32 vcc, s49, v132
	v_mul_f32_e32 v133, 0x4b800000, v132
	s_add_i32 s51, s51, 1
	v_cndmask_b32_e32 v132, v132, v133, vcc
	v_rsq_f32_e32 v132, v132
	s_nop 0
	v_mul_f32_e32 v133, 0x45800000, v132
	v_cndmask_b32_e32 v134, v132, v133, vcc
	v_mov_b32_e32 v132, v129
	v_mov_b32_e32 v133, v130
	v_mov_b32_e32 v129, v131
	v_pk_add_f32 v[128:129], v[132:133], v[128:129]
	v_and_b32_e32 v131, 64, v178
	v_add_f32_e32 v128, v128, v129
	v_mul_f32_e32 v129, v134, v134
	v_mul_f32_e32 v128, v128, v129
	v_fmamk_f32 v128, v128, 0x3b800000, v180
	v_cmp_gt_f32_e32 vcc, s49, v128
	v_mul_f32_e32 v129, 0x4b800000, v128
	v_add_u32_e32 v131, 64, v131
	v_cndmask_b32_e32 v128, v128, v129, vcc
	v_rsq_f32_e32 v128, v128
	s_nop 0
	v_mul_f32_e32 v129, 0x45800000, v128
	v_cndmask_b32_e32 v128, v128, v129, vcc
	v_max3_f32 v129, v112, s50, v113
	v_max3_f32 v129, v129, v114, v115
	v_max3_f32 v129, v129, v116, v117
	v_max3_f32 v129, v129, v118, v119
	v_max3_f32 v129, v129, v120, v121
	v_max3_f32 v129, v129, v122, v123
	v_max3_f32 v129, v129, v124, v125
	v_max3_f32 v129, v129, v126, v127
	v_max3_f32 v129, v129, v96, v97
	v_max3_f32 v129, v129, v98, v99
	v_max3_f32 v129, v129, v100, v101
	v_max3_f32 v129, v129, v102, v103
	v_max3_f32 v129, v129, v104, v105
	v_max3_f32 v129, v129, v106, v107
	v_max3_f32 v129, v129, v108, v109
	v_max3_f32 v129, v129, v110, v111
	v_max3_f32 v129, v129, v80, v81
	v_max3_f32 v129, v129, v82, v83
	v_max3_f32 v129, v129, v84, v85
	v_max3_f32 v129, v129, v86, v87
	v_max3_f32 v129, v129, v88, v89
	v_max3_f32 v129, v129, v90, v91
	v_max3_f32 v129, v129, v92, v93
	v_max3_f32 v129, v129, v94, v95
	v_max3_f32 v129, v129, v64, v65
	v_max3_f32 v129, v129, v66, v67
	v_max3_f32 v129, v129, v68, v69
	v_max3_f32 v129, v129, v70, v71
	v_max3_f32 v129, v129, v72, v73
	v_max3_f32 v129, v129, v74, v75
	v_max3_f32 v129, v129, v76, v77
	v_max3_f32 v129, v129, v78, v79
	v_max3_f32 v129, v129, v48, v49
	v_max3_f32 v129, v129, v50, v51
	v_max3_f32 v129, v129, v52, v53
	v_max3_f32 v129, v129, v54, v55
	v_max3_f32 v129, v129, v56, v57
	v_max3_f32 v129, v129, v58, v59
	v_max3_f32 v129, v129, v60, v61
	v_max3_f32 v129, v129, v62, v63
	v_max3_f32 v129, v129, v32, v33
	v_max3_f32 v129, v129, v34, v35
	v_max3_f32 v129, v129, v36, v37
	v_max3_f32 v129, v129, v38, v39
	v_max3_f32 v129, v129, v40, v41
	v_max3_f32 v129, v129, v42, v43
	v_max3_f32 v129, v129, v44, v45
	v_max3_f32 v129, v129, v46, v47
	v_max3_f32 v129, v129, v16, v17
	v_max3_f32 v129, v129, v18, v19
	v_max3_f32 v129, v129, v20, v21
	v_max3_f32 v129, v129, v22, v23
	v_max3_f32 v129, v129, v24, v25
	v_max3_f32 v129, v129, v26, v27
	v_max3_f32 v129, v129, v28, v29
	v_max3_f32 v129, v129, v30, v31
	v_max3_f32 v129, v129, v0, v1
	v_max3_f32 v129, v129, v2, v3
	v_max3_f32 v129, v129, v4, v5
	v_max3_f32 v129, v129, v6, v7
	v_max3_f32 v129, v129, v8, v9
	v_max3_f32 v129, v129, v10, v11
	v_mul_f32_e32 v128, v134, v128
	v_max3_f32 v129, v129, v12, v13
	v_max3_f32 v130, v129, v14, v15
	v_mul_f32_e32 v129, 0x3db8aa3b, v128
	v_xor_b32_e32 v128, 32, v178
	v_cmp_lt_i32_e32 vcc, v128, v131
	v_mul_f32_e32 v130, v129, v130
	s_nop 0
	v_cndmask_b32_e32 v128, v178, v128, vcc
	v_lshlrev_b32_e32 v128, 2, v128
	ds_bpermute_b32 v131, v128, v130
	s_waitcnt lgkmcnt(0)
	v_max_f32_e32 v131, v131, v131
	v_max_f32_e32 v130, v130, v131
	v_pk_fma_f32 v[112:113], v[112:113], v[128:129], v[130:131] op_sel:[0,1,0] op_sel_hi:[1,1,0] neg_lo:[0,0,1] neg_hi:[0,0,1]
	v_exp_f32_e32 v112, v112
	v_exp_f32_e32 v113, v113
	v_pk_fma_f32 v[114:115], v[114:115], v[128:129], v[130:131] op_sel:[0,1,0] op_sel_hi:[1,1,0] neg_lo:[0,0,1] neg_hi:[0,0,1]
	v_exp_f32_e32 v114, v114
	v_exp_f32_e32 v115, v115
	v_fma_f32 v116, v129, v116, -v130
	v_add_f32_e32 v131, 0, v112
	v_exp_f32_e32 v132, v116
	v_add_f32_e32 v131, v113, v131
	v_add_f32_e32 v131, v114, v131
	v_add_f32_e32 v131, v115, v131
	v_fma_f32 v117, v129, v117, -v130
	v_add_f32_e32 v116, v132, v131
	v_exp_f32_e32 v131, v117
	v_pk_fma_f32 v[118:119], v[118:119], v[128:129], v[130:131] op_sel:[0,1,0] op_sel_hi:[1,1,0] neg_lo:[0,0,1] neg_hi:[0,0,1]
	v_exp_f32_e32 v133, v118
	v_exp_f32_e32 v119, v119
	v_pk_fma_f32 v[120:121], v[120:121], v[128:129], v[130:131] op_sel:[0,1,0] op_sel_hi:[1,1,0] neg_lo:[0,0,1] neg_hi:[0,0,1]
	v_exp_f32_e32 v120, v120
	v_add_f32_e32 v116, v131, v116
	v_exp_f32_e32 v121, v121
	v_pk_fma_f32 v[122:123], v[122:123], v[128:129], v[130:131] op_sel:[0,1,0] op_sel_hi:[1,1,0] neg_lo:[0,0,1] neg_hi:[0,0,1]
	v_add_f32_e32 v116, v133, v116
	v_exp_f32_e32 v122, v122
	v_add_f32_e32 v116, v119, v116
	v_exp_f32_e32 v123, v123
	v_pk_fma_f32 v[124:125], v[124:125], v[128:129], v[130:131] op_sel:[0,1,0] op_sel_hi:[1,1,0] neg_lo:[0,0,1] neg_hi:[0,0,1]
	v_add_f32_e32 v116, v120, v116
	v_exp_f32_e32 v124, v124
	v_add_f32_e32 v116, v121, v116
	v_exp_f32_e32 v125, v125
	v_pk_fma_f32 v[126:127], v[126:127], v[128:129], v[130:131] op_sel:[0,1,0] op_sel_hi:[1,1,0] neg_lo:[0,0,1] neg_hi:[0,0,1]
	v_add_f32_e32 v116, v122, v116
	v_exp_f32_e32 v126, v126
	v_add_f32_e32 v116, v123, v116
	v_exp_f32_e32 v127, v127
	v_pk_fma_f32 v[96:97], v[96:97], v[128:129], v[130:131] op_sel:[0,1,0] op_sel_hi:[1,1,0] neg_lo:[0,0,1] neg_hi:[0,0,1]
	v_add_f32_e32 v116, v124, v116
	v_exp_f32_e32 v96, v96
	v_add_f32_e32 v116, v125, v116
	v_exp_f32_e32 v97, v97
	v_pk_fma_f32 v[98:99], v[98:99], v[128:129], v[130:131] op_sel:[0,1,0] op_sel_hi:[1,1,0] neg_lo:[0,0,1] neg_hi:[0,0,1]
	v_add_f32_e32 v116, v126, v116
	v_exp_f32_e32 v98, v98
	v_add_f32_e32 v134, v127, v116
	v_exp_f32_e32 v99, v99
	v_fma_f32 v100, v129, v100, -v130
	v_cvt_pk_bf16_f32 v116, v112, v113
	v_cvt_pk_bf16_f32 v112, v120, v121
	v_add_f32_e32 v120, v96, v134
	v_exp_f32_e32 v121, v100
	v_add_f32_e32 v120, v97, v120
	v_add_f32_e32 v120, v98, v120
	v_add_f32_e32 v120, v99, v120
	v_fma_f32 v101, v129, v101, -v130
	v_add_f32_e32 v100, v121, v120
	v_exp_f32_e32 v120, v101
	v_pk_fma_f32 v[102:103], v[102:103], v[128:129], v[130:131] op_sel:[0,1,0] op_sel_hi:[1,1,0] neg_lo:[0,0,1] neg_hi:[0,0,1]
	v_cvt_pk_bf16_f32 v113, v122, v123
	v_exp_f32_e32 v122, v102
	v_exp_f32_e32 v103, v103
	v_pk_fma_f32 v[104:105], v[104:105], v[128:129], v[130:131] op_sel:[0,1,0] op_sel_hi:[1,1,0] neg_lo:[0,0,1] neg_hi:[0,0,1]
	v_exp_f32_e32 v104, v104
	v_add_f32_e32 v100, v120, v100
	v_exp_f32_e32 v105, v105
	v_pk_fma_f32 v[106:107], v[106:107], v[128:129], v[130:131] op_sel:[0,1,0] op_sel_hi:[1,1,0] neg_lo:[0,0,1] neg_hi:[0,0,1]
	v_add_f32_e32 v100, v122, v100
	v_exp_f32_e32 v106, v106
	v_add_f32_e32 v100, v103, v100
	v_exp_f32_e32 v107, v107
	v_pk_fma_f32 v[108:109], v[108:109], v[128:129], v[130:131] op_sel:[0,1,0] op_sel_hi:[1,1,0] neg_lo:[0,0,1] neg_hi:[0,0,1]
	v_add_f32_e32 v100, v104, v100
	v_exp_f32_e32 v108, v108
	v_add_f32_e32 v100, v105, v100
	v_exp_f32_e32 v109, v109
	v_pk_fma_f32 v[110:111], v[110:111], v[128:129], v[130:131] op_sel:[0,1,0] op_sel_hi:[1,1,0] neg_lo:[0,0,1] neg_hi:[0,0,1]
	v_add_f32_e32 v100, v106, v100
	v_exp_f32_e32 v110, v110
	v_add_f32_e32 v100, v107, v100
	v_exp_f32_e32 v111, v111
	v_pk_fma_f32 v[80:81], v[80:81], v[128:129], v[130:131] op_sel:[0,1,0] op_sel_hi:[1,1,0] neg_lo:[0,0,1] neg_hi:[0,0,1]
	v_add_f32_e32 v100, v108, v100
	v_exp_f32_e32 v80, v80
	v_add_f32_e32 v100, v109, v100
	v_exp_f32_e32 v81, v81
	v_pk_fma_f32 v[82:83], v[82:83], v[128:129], v[130:131] op_sel:[0,1,0] op_sel_hi:[1,1,0] neg_lo:[0,0,1] neg_hi:[0,0,1]
	v_add_f32_e32 v100, v110, v100
	v_exp_f32_e32 v82, v82
	v_add_f32_e32 v123, v111, v100
	v_exp_f32_e32 v83, v83
	v_fma_f32 v84, v129, v84, -v130
	v_cvt_pk_bf16_f32 v100, v96, v97
	v_cvt_pk_bf16_f32 v96, v104, v105
	v_add_f32_e32 v104, v80, v123
	v_exp_f32_e32 v105, v84
	v_add_f32_e32 v104, v81, v104
	v_add_f32_e32 v104, v82, v104
	v_add_f32_e32 v104, v83, v104
	v_fma_f32 v85, v129, v85, -v130
	v_add_f32_e32 v84, v105, v104
	v_exp_f32_e32 v104, v85
	v_pk_fma_f32 v[86:87], v[86:87], v[128:129], v[130:131] op_sel:[0,1,0] op_sel_hi:[1,1,0] neg_lo:[0,0,1] neg_hi:[0,0,1]
	v_cvt_pk_bf16_f32 v97, v106, v107
	v_exp_f32_e32 v106, v86
	v_exp_f32_e32 v87, v87
	v_pk_fma_f32 v[88:89], v[88:89], v[128:129], v[130:131] op_sel:[0,1,0] op_sel_hi:[1,1,0] neg_lo:[0,0,1] neg_hi:[0,0,1]
	v_exp_f32_e32 v88, v88
	v_add_f32_e32 v84, v104, v84
	v_exp_f32_e32 v89, v89
	v_pk_fma_f32 v[90:91], v[90:91], v[128:129], v[130:131] op_sel:[0,1,0] op_sel_hi:[1,1,0] neg_lo:[0,0,1] neg_hi:[0,0,1]
	v_add_f32_e32 v84, v106, v84
	v_exp_f32_e32 v90, v90
	v_add_f32_e32 v84, v87, v84
	v_exp_f32_e32 v91, v91
	v_pk_fma_f32 v[92:93], v[92:93], v[128:129], v[130:131] op_sel:[0,1,0] op_sel_hi:[1,1,0] neg_lo:[0,0,1] neg_hi:[0,0,1]
	v_add_f32_e32 v84, v88, v84
	v_exp_f32_e32 v92, v92
	v_add_f32_e32 v84, v89, v84
	v_exp_f32_e32 v93, v93
	v_pk_fma_f32 v[94:95], v[94:95], v[128:129], v[130:131] op_sel:[0,1,0] op_sel_hi:[1,1,0] neg_lo:[0,0,1] neg_hi:[0,0,1]
	v_add_f32_e32 v84, v90, v84
	v_exp_f32_e32 v94, v94
	v_add_f32_e32 v84, v91, v84
	v_exp_f32_e32 v95, v95
	v_pk_fma_f32 v[64:65], v[64:65], v[128:129], v[130:131] op_sel:[0,1,0] op_sel_hi:[1,1,0] neg_lo:[0,0,1] neg_hi:[0,0,1]
	v_add_f32_e32 v84, v92, v84
	v_exp_f32_e32 v64, v64
	v_add_f32_e32 v84, v93, v84
	v_exp_f32_e32 v65, v65
	v_pk_fma_f32 v[66:67], v[66:67], v[128:129], v[130:131] op_sel:[0,1,0] op_sel_hi:[1,1,0] neg_lo:[0,0,1] neg_hi:[0,0,1]
	v_add_f32_e32 v84, v94, v84
	v_exp_f32_e32 v66, v66
	v_add_f32_e32 v107, v95, v84
	v_exp_f32_e32 v67, v67
	v_fma_f32 v68, v129, v68, -v130
	v_cvt_pk_bf16_f32 v84, v80, v81
	v_cvt_pk_bf16_f32 v80, v88, v89
	v_add_f32_e32 v88, v64, v107
	v_exp_f32_e32 v89, v68
	v_add_f32_e32 v88, v65, v88
	v_add_f32_e32 v88, v66, v88
	v_add_f32_e32 v88, v67, v88
	v_fma_f32 v69, v129, v69, -v130
	v_add_f32_e32 v68, v89, v88
	v_exp_f32_e32 v88, v69
	v_pk_fma_f32 v[70:71], v[70:71], v[128:129], v[130:131] op_sel:[0,1,0] op_sel_hi:[1,1,0] neg_lo:[0,0,1] neg_hi:[0,0,1]
	v_cvt_pk_bf16_f32 v81, v90, v91
	v_exp_f32_e32 v90, v70
	v_exp_f32_e32 v71, v71
	v_pk_fma_f32 v[72:73], v[72:73], v[128:129], v[130:131] op_sel:[0,1,0] op_sel_hi:[1,1,0] neg_lo:[0,0,1] neg_hi:[0,0,1]
	v_exp_f32_e32 v72, v72
	v_add_f32_e32 v68, v88, v68
	v_exp_f32_e32 v73, v73
	v_pk_fma_f32 v[74:75], v[74:75], v[128:129], v[130:131] op_sel:[0,1,0] op_sel_hi:[1,1,0] neg_lo:[0,0,1] neg_hi:[0,0,1]
	v_add_f32_e32 v68, v90, v68
	v_exp_f32_e32 v74, v74
	v_add_f32_e32 v68, v71, v68
	v_exp_f32_e32 v75, v75
	v_pk_fma_f32 v[76:77], v[76:77], v[128:129], v[130:131] op_sel:[0,1,0] op_sel_hi:[1,1,0] neg_lo:[0,0,1] neg_hi:[0,0,1]
	v_add_f32_e32 v68, v72, v68
	v_exp_f32_e32 v76, v76
	v_add_f32_e32 v68, v73, v68
	v_exp_f32_e32 v77, v77
	v_pk_fma_f32 v[78:79], v[78:79], v[128:129], v[130:131] op_sel:[0,1,0] op_sel_hi:[1,1,0] neg_lo:[0,0,1] neg_hi:[0,0,1]
	v_add_f32_e32 v68, v74, v68
	v_exp_f32_e32 v78, v78
	v_add_f32_e32 v68, v75, v68
	v_exp_f32_e32 v79, v79
	v_pk_fma_f32 v[48:49], v[48:49], v[128:129], v[130:131] op_sel:[0,1,0] op_sel_hi:[1,1,0] neg_lo:[0,0,1] neg_hi:[0,0,1]
	v_add_f32_e32 v68, v76, v68
	v_exp_f32_e32 v48, v48
	v_add_f32_e32 v68, v77, v68
	v_exp_f32_e32 v49, v49
	v_pk_fma_f32 v[50:51], v[50:51], v[128:129], v[130:131] op_sel:[0,1,0] op_sel_hi:[1,1,0] neg_lo:[0,0,1] neg_hi:[0,0,1]
	v_add_f32_e32 v68, v78, v68
	v_exp_f32_e32 v50, v50
	v_add_f32_e32 v91, v79, v68
	v_exp_f32_e32 v51, v51
	v_fma_f32 v52, v129, v52, -v130
	v_cvt_pk_bf16_f32 v68, v64, v65
	v_cvt_pk_bf16_f32 v64, v72, v73
	v_add_f32_e32 v72, v48, v91
	v_exp_f32_e32 v73, v52
	v_add_f32_e32 v72, v49, v72
	v_add_f32_e32 v72, v50, v72
	v_add_f32_e32 v72, v51, v72
	v_fma_f32 v53, v129, v53, -v130
	v_add_f32_e32 v52, v73, v72
	v_exp_f32_e32 v72, v53
	v_pk_fma_f32 v[54:55], v[54:55], v[128:129], v[130:131] op_sel:[0,1,0] op_sel_hi:[1,1,0] neg_lo:[0,0,1] neg_hi:[0,0,1]
	v_cvt_pk_bf16_f32 v65, v74, v75
	v_exp_f32_e32 v74, v54
	v_exp_f32_e32 v55, v55
	v_pk_fma_f32 v[56:57], v[56:57], v[128:129], v[130:131] op_sel:[0,1,0] op_sel_hi:[1,1,0] neg_lo:[0,0,1] neg_hi:[0,0,1]
	v_exp_f32_e32 v56, v56
	v_add_f32_e32 v52, v72, v52
	v_exp_f32_e32 v57, v57
	v_pk_fma_f32 v[58:59], v[58:59], v[128:129], v[130:131] op_sel:[0,1,0] op_sel_hi:[1,1,0] neg_lo:[0,0,1] neg_hi:[0,0,1]
	v_add_f32_e32 v52, v74, v52
	v_exp_f32_e32 v58, v58
	v_add_f32_e32 v52, v55, v52
	v_exp_f32_e32 v59, v59
	v_pk_fma_f32 v[60:61], v[60:61], v[128:129], v[130:131] op_sel:[0,1,0] op_sel_hi:[1,1,0] neg_lo:[0,0,1] neg_hi:[0,0,1]
	v_add_f32_e32 v52, v56, v52
	v_exp_f32_e32 v60, v60
	v_add_f32_e32 v52, v57, v52
	v_exp_f32_e32 v61, v61
	v_pk_fma_f32 v[62:63], v[62:63], v[128:129], v[130:131] op_sel:[0,1,0] op_sel_hi:[1,1,0] neg_lo:[0,0,1] neg_hi:[0,0,1]
	v_add_f32_e32 v52, v58, v52
	v_exp_f32_e32 v62, v62
	v_add_f32_e32 v52, v59, v52
	v_exp_f32_e32 v63, v63
	v_pk_fma_f32 v[32:33], v[32:33], v[128:129], v[130:131] op_sel:[0,1,0] op_sel_hi:[1,1,0] neg_lo:[0,0,1] neg_hi:[0,0,1]
	v_add_f32_e32 v52, v60, v52
	v_exp_f32_e32 v32, v32
	v_add_f32_e32 v52, v61, v52
	v_exp_f32_e32 v33, v33
	v_pk_fma_f32 v[34:35], v[34:35], v[128:129], v[130:131] op_sel:[0,1,0] op_sel_hi:[1,1,0] neg_lo:[0,0,1] neg_hi:[0,0,1]
	v_add_f32_e32 v52, v62, v52
	v_exp_f32_e32 v34, v34
	v_add_f32_e32 v75, v63, v52
	v_exp_f32_e32 v35, v35
	v_fma_f32 v36, v129, v36, -v130
	v_cvt_pk_bf16_f32 v52, v48, v49
	v_cvt_pk_bf16_f32 v48, v56, v57
	v_add_f32_e32 v56, v32, v75
	v_exp_f32_e32 v57, v36
	v_add_f32_e32 v56, v33, v56
	v_add_f32_e32 v56, v34, v56
	v_add_f32_e32 v56, v35, v56
	v_fma_f32 v37, v129, v37, -v130
	v_add_f32_e32 v36, v57, v56
	v_exp_f32_e32 v56, v37
	v_pk_fma_f32 v[38:39], v[38:39], v[128:129], v[130:131] op_sel:[0,1,0] op_sel_hi:[1,1,0] neg_lo:[0,0,1] neg_hi:[0,0,1]
	v_cvt_pk_bf16_f32 v49, v58, v59
	v_exp_f32_e32 v58, v38
	v_exp_f32_e32 v39, v39
	v_pk_fma_f32 v[40:41], v[40:41], v[128:129], v[130:131] op_sel:[0,1,0] op_sel_hi:[1,1,0] neg_lo:[0,0,1] neg_hi:[0,0,1]
	v_exp_f32_e32 v40, v40
	v_add_f32_e32 v36, v56, v36
	v_exp_f32_e32 v41, v41
	v_pk_fma_f32 v[42:43], v[42:43], v[128:129], v[130:131] op_sel:[0,1,0] op_sel_hi:[1,1,0] neg_lo:[0,0,1] neg_hi:[0,0,1]
	v_add_f32_e32 v36, v58, v36
	v_exp_f32_e32 v42, v42
	v_add_f32_e32 v36, v39, v36
	v_exp_f32_e32 v43, v43
	v_pk_fma_f32 v[44:45], v[44:45], v[128:129], v[130:131] op_sel:[0,1,0] op_sel_hi:[1,1,0] neg_lo:[0,0,1] neg_hi:[0,0,1]
	v_add_f32_e32 v36, v40, v36
	v_exp_f32_e32 v44, v44
	v_add_f32_e32 v36, v41, v36
	v_exp_f32_e32 v45, v45
	v_pk_fma_f32 v[46:47], v[46:47], v[128:129], v[130:131] op_sel:[0,1,0] op_sel_hi:[1,1,0] neg_lo:[0,0,1] neg_hi:[0,0,1]
	v_add_f32_e32 v36, v42, v36
	v_exp_f32_e32 v46, v46
	v_add_f32_e32 v36, v43, v36
	v_exp_f32_e32 v47, v47
	v_pk_fma_f32 v[16:17], v[16:17], v[128:129], v[130:131] op_sel:[0,1,0] op_sel_hi:[1,1,0] neg_lo:[0,0,1] neg_hi:[0,0,1]
	v_add_f32_e32 v36, v44, v36
	v_exp_f32_e32 v16, v16
	v_add_f32_e32 v36, v45, v36
	v_exp_f32_e32 v17, v17
	v_pk_fma_f32 v[18:19], v[18:19], v[128:129], v[130:131] op_sel:[0,1,0] op_sel_hi:[1,1,0] neg_lo:[0,0,1] neg_hi:[0,0,1]
	v_add_f32_e32 v36, v46, v36
	v_exp_f32_e32 v18, v18
	v_add_f32_e32 v59, v47, v36
	v_exp_f32_e32 v19, v19
	v_fma_f32 v20, v129, v20, -v130
	v_cvt_pk_bf16_f32 v36, v32, v33
	v_cvt_pk_bf16_f32 v32, v40, v41
	v_add_f32_e32 v40, v16, v59
	v_exp_f32_e32 v41, v20
	v_add_f32_e32 v40, v17, v40
	v_add_f32_e32 v40, v18, v40
	v_add_f32_e32 v40, v19, v40
	v_fma_f32 v21, v129, v21, -v130
	v_add_f32_e32 v20, v41, v40
	v_exp_f32_e32 v40, v21
	v_pk_fma_f32 v[22:23], v[22:23], v[128:129], v[130:131] op_sel:[0,1,0] op_sel_hi:[1,1,0] neg_lo:[0,0,1] neg_hi:[0,0,1]
	v_cvt_pk_bf16_f32 v33, v42, v43
	v_exp_f32_e32 v42, v22
	v_exp_f32_e32 v23, v23
	v_pk_fma_f32 v[24:25], v[24:25], v[128:129], v[130:131] op_sel:[0,1,0] op_sel_hi:[1,1,0] neg_lo:[0,0,1] neg_hi:[0,0,1]
	v_exp_f32_e32 v24, v24
	v_add_f32_e32 v20, v40, v20
	v_exp_f32_e32 v25, v25
	v_pk_fma_f32 v[26:27], v[26:27], v[128:129], v[130:131] op_sel:[0,1,0] op_sel_hi:[1,1,0] neg_lo:[0,0,1] neg_hi:[0,0,1]
	v_add_f32_e32 v20, v42, v20
	v_exp_f32_e32 v26, v26
	v_add_f32_e32 v20, v23, v20
	v_exp_f32_e32 v27, v27
	v_pk_fma_f32 v[28:29], v[28:29], v[128:129], v[130:131] op_sel:[0,1,0] op_sel_hi:[1,1,0] neg_lo:[0,0,1] neg_hi:[0,0,1]
	v_add_f32_e32 v20, v24, v20
	v_exp_f32_e32 v28, v28
	v_add_f32_e32 v20, v25, v20
	v_exp_f32_e32 v29, v29
	v_pk_fma_f32 v[30:31], v[30:31], v[128:129], v[130:131] op_sel:[0,1,0] op_sel_hi:[1,1,0] neg_lo:[0,0,1] neg_hi:[0,0,1]
	v_add_f32_e32 v20, v26, v20
	v_exp_f32_e32 v30, v30
	v_add_f32_e32 v20, v27, v20
	v_exp_f32_e32 v31, v31
	v_pk_fma_f32 v[0:1], v[0:1], v[128:129], v[130:131] op_sel:[0,1,0] op_sel_hi:[1,1,0] neg_lo:[0,0,1] neg_hi:[0,0,1]
	v_add_f32_e32 v20, v28, v20
	v_exp_f32_e32 v0, v0
	v_add_f32_e32 v20, v29, v20
	v_exp_f32_e32 v1, v1
	v_pk_fma_f32 v[2:3], v[2:3], v[128:129], v[130:131] op_sel:[0,1,0] op_sel_hi:[1,1,0] neg_lo:[0,0,1] neg_hi:[0,0,1]
	v_add_f32_e32 v20, v30, v20
	v_exp_f32_e32 v2, v2
	v_add_f32_e32 v43, v31, v20
	v_exp_f32_e32 v3, v3
	v_pk_fma_f32 v[4:5], v[4:5], v[128:129], v[130:131] op_sel:[0,1,0] op_sel_hi:[1,1,0] neg_lo:[0,0,1] neg_hi:[0,0,1]
	v_cvt_pk_bf16_f32 v20, v16, v17
	v_cvt_pk_bf16_f32 v16, v24, v25
	v_add_f32_e32 v24, v0, v43
	v_exp_f32_e32 v4, v4
	v_add_f32_e32 v24, v1, v24
	v_exp_f32_e32 v5, v5
	v_pk_fma_f32 v[6:7], v[6:7], v[128:129], v[130:131] op_sel:[0,1,0] op_sel_hi:[1,1,0] neg_lo:[0,0,1] neg_hi:[0,0,1]
	v_add_f32_e32 v24, v2, v24
	v_exp_f32_e32 v6, v6
	v_add_f32_e32 v24, v3, v24
	v_exp_f32_e32 v7, v7
	v_pk_fma_f32 v[8:9], v[8:9], v[128:129], v[130:131] op_sel:[0,1,0] op_sel_hi:[1,1,0] neg_lo:[0,0,1] neg_hi:[0,0,1]
	v_add_f32_e32 v24, v4, v24
	v_exp_f32_e32 v8, v8
	v_add_f32_e32 v24, v5, v24
	v_exp_f32_e32 v9, v9
	v_pk_fma_f32 v[10:11], v[10:11], v[128:129], v[130:131] op_sel:[0,1,0] op_sel_hi:[1,1,0] neg_lo:[0,0,1] neg_hi:[0,0,1]
	v_add_f32_e32 v24, v6, v24
	v_exp_f32_e32 v10, v10
	v_add_f32_e32 v24, v7, v24
	v_exp_f32_e32 v11, v11
	v_pk_fma_f32 v[12:13], v[12:13], v[128:129], v[130:131] op_sel:[0,1,0] op_sel_hi:[1,1,0] neg_lo:[0,0,1] neg_hi:[0,0,1]
	v_add_f32_e32 v24, v8, v24
	v_exp_f32_e32 v12, v12
	v_add_f32_e32 v24, v9, v24
	v_exp_f32_e32 v13, v13
	v_pk_fma_f32 v[14:15], v[14:15], v[128:129], v[130:131] op_sel:[0,1,0] op_sel_hi:[1,1,0] neg_lo:[0,0,1] neg_hi:[0,0,1]
	v_add_f32_e32 v24, v10, v24
	v_exp_f32_e32 v14, v14
	v_add_f32_e32 v24, v11, v24
	v_exp_f32_e32 v15, v15
	v_add_f32_e32 v24, v12, v24
	v_add_f32_e32 v24, v13, v24
	v_add_f32_e32 v24, v14, v24
	v_cvt_pk_bf16_f32 v22, v41, v40
	v_add_f32_e32 v40, v15, v24
	v_cvt_pk_bf16_f32 v21, v18, v19
	v_cvt_pk_bf16_f32 v18, v28, v29
	v_cvt_pk_bf16_f32 v28, v0, v1
	ds_bpermute_b32 v0, v128, v40
	v_cvt_pk_bf16_f32 v117, v114, v115
	v_cvt_pk_bf16_f32 v118, v132, v131
	v_cvt_pk_bf16_f32 v119, v133, v119
	v_cvt_pk_bf16_f32 v114, v124, v125
	v_cvt_pk_bf16_f32 v115, v126, v127
	v_cvt_pk_bf16_f32 v101, v98, v99
	v_cvt_pk_bf16_f32 v102, v121, v120
	v_cvt_pk_bf16_f32 v103, v122, v103
	v_cvt_pk_bf16_f32 v98, v108, v109
	v_cvt_pk_bf16_f32 v99, v110, v111
	v_cvt_pk_bf16_f32 v85, v82, v83
	v_cvt_pk_bf16_f32 v86, v105, v104
	v_cvt_pk_bf16_f32 v87, v106, v87
	v_cvt_pk_bf16_f32 v82, v92, v93
	v_cvt_pk_bf16_f32 v83, v94, v95
	v_cvt_pk_bf16_f32 v69, v66, v67
	v_cvt_pk_bf16_f32 v70, v89, v88
	v_cvt_pk_bf16_f32 v71, v90, v71
	v_cvt_pk_bf16_f32 v66, v76, v77
	v_cvt_pk_bf16_f32 v67, v78, v79
	v_cvt_pk_bf16_f32 v53, v50, v51
	v_cvt_pk_bf16_f32 v54, v73, v72
	v_cvt_pk_bf16_f32 v55, v74, v55
	v_cvt_pk_bf16_f32 v50, v60, v61
	v_cvt_pk_bf16_f32 v51, v62, v63
	v_cvt_pk_bf16_f32 v37, v34, v35
	v_cvt_pk_bf16_f32 v38, v57, v56
	v_cvt_pk_bf16_f32 v39, v58, v39
	v_cvt_pk_bf16_f32 v34, v44, v45
	v_cvt_pk_bf16_f32 v35, v46, v47
	v_cvt_pk_bf16_f32 v23, v42, v23
	v_cvt_pk_bf16_f32 v17, v26, v27
	v_cvt_pk_bf16_f32 v19, v30, v31
	v_cvt_pk_bf16_f32 v29, v2, v3
	v_cvt_pk_bf16_f32 v30, v4, v5
	v_cvt_pk_bf16_f32 v31, v6, v7
	v_cvt_pk_bf16_f32 v24, v8, v9
	v_cvt_pk_bf16_f32 v25, v10, v11
	v_cvt_pk_bf16_f32 v26, v12, v13
	v_cvt_pk_bf16_f32 v27, v14, v15
	v_lshl_add_u64 v[60:61], v[160:161], 0, s[38:39]
	s_waitcnt lgkmcnt(0)
	v_add_f32_e32 v72, v40, v0
	s_barrier
	s_waitcnt vmcnt(0)
	ds_write_b128 v172, v[228:231]
	ds_write_b128 v172, v[224:227] offset:128
	ds_write_b128 v172, v[216:219] offset:256
	ds_write_b128 v172, v[212:215] offset:384
	ds_write_b128 v172, v[232:235] offset:35840
	ds_write_b128 v172, v[246:249] offset:35968
	ds_write_b128 v172, v[240:243] offset:36096
	ds_write_b128 v172, v[236:239] offset:36224
	v_lshl_add_u64 v[12:13], v[160:161], 0, s[40:41]
	v_lshl_add_u64 v[60:61], v[160:161], 0, s[44:45]
	global_load_dwordx4 v[0:3], v[164:165], off offset:2048
	global_load_dwordx4 v[4:7], v[12:13], off offset:384
	global_load_dwordx4 v[8:11], v[12:13], off offset:256
	s_nop 0
	global_load_dwordx4 v[12:15], v[12:13], off offset:128
	s_nop 0
	global_load_dwordx4 v[40:43], v[166:167], off offset:2048
	global_load_dwordx4 v[44:47], v[60:61], off offset:384
	global_load_dwordx4 v[56:59], v[60:61], off offset:256
	s_nop 0
	global_load_dwordx4 v[60:63], v[60:61], off offset:128
	s_waitcnt vmcnt(7)
	ds_write_b128 v173, v[0:3]
	s_waitcnt vmcnt(4)
	ds_write_b128 v174, v[12:15]
	ds_write_b128 v175, v[8:11]
	ds_write_b128 v179, v[4:7]
	s_waitcnt vmcnt(3)
	ds_write_b128 v182, v[40:43]
	s_waitcnt vmcnt(0)
	ds_write_b128 v183, v[60:63]
	ds_write_b128 v184, v[56:59]
	ds_write_b128 v185, v[44:47]
	v_div_scale_f32 v0, s[4:5], v72, v72, 1.0
	v_rcp_f32_e32 v1, v0
	s_waitcnt lgkmcnt(0)
	s_barrier
	v_fma_f32 v2, -v0, v1, 1.0
	v_fmac_f32_e32 v1, v2, v1
	v_div_scale_f32 v2, vcc, 1.0, v72, 1.0
	v_mul_f32_e32 v3, v2, v1
	v_fma_f32 v4, -v0, v3, v2
	v_fmac_f32_e32 v3, v4, v1
	v_fma_f32 v0, -v0, v3, v2
	v_div_fmas_f32 v0, v0, v1, v3
	v_div_fixup_f32 v44, v0, v72, 1.0
	v_lshl_add_u64 v[0:1], s[12:13], 0, v[162:163]
	v_lshl_add_u64 v[0:1], v[0:1], 0, s[10:11]
	v_lshl_add_u64 v[46:47], v[0:1], 0, v[158:159]
	v_mbcnt_lo_u32_b32 v40, -1, 0
	v_mbcnt_hi_u32_b32 v40, -1, v40
	v_and_b32_e32 v40, 32, v40
	v_lshrrev_b32_e32 v40, 2, v40
	v_mov_b32_e32 v41, 0
	v_lshl_add_u64 v[124:125], v[46:47], 0, v[40:41]
	ds_read_b64_tr_b16 v[56:57], v186
	ds_read_b64_tr_b16 v[58:59], v186 offset:4480
	ds_read_b64_tr_b16 v[60:61], v186 offset:8960
	ds_read_b64_tr_b16 v[62:63], v186 offset:13440
	ds_read_b64_tr_b16 v[88:89], v186 offset:17920
	ds_read_b64_tr_b16 v[90:91], v186 offset:22400
	ds_read_b64_tr_b16 v[92:93], v186 offset:26880
	ds_read_b64_tr_b16 v[94:95], v186 offset:31360
	ds_read_b64_tr_b16 v[104:105], v186 offset:35840
	ds_read_b64_tr_b16 v[106:107], v186 offset:40320
	ds_read_b64_tr_b16 v[108:109], v186 offset:44800
	ds_read_b64_tr_b16 v[110:111], v186 offset:49280
	ds_read_b64_tr_b16 v[120:121], v186 offset:53760
	ds_read_b64_tr_b16 v[122:123], v186 offset:58240
	s_mov_b64 s[4:5], 0
	s_waitcnt lgkmcnt(12)
	v_mfma_f32_32x32x16_bf16 v[0:15], v[56:59], v[116:119], 0
	v_add_u32_e32 v40, v187, v177
	ds_read_b64_tr_b16 v[56:57], v186 offset:62720
	ds_read_b64_tr_b16 v[58:59], v40
	s_waitcnt lgkmcnt(12)
	v_mfma_f32_32x32x16_bf16 v[0:15], v[60:63], v[112:115], v[0:15]
	v_add_u32_e32 v40, v188, v177
	v_add_u32_e32 v42, v189, v177
	ds_read_b64_tr_b16 v[60:61], v40
	ds_read_b64_tr_b16 v[62:63], v42
	s_waitcnt lgkmcnt(12)
	v_mfma_f32_32x32x16_bf16 v[0:15], v[88:91], v[100:103], v[0:15]
	v_add_u32_e32 v40, v190, v177
	v_add_u32_e32 v42, v191, v177
	ds_read_b64_tr_b16 v[88:89], v40
	ds_read_b64_tr_b16 v[90:91], v42
	s_waitcnt lgkmcnt(12)
	v_mfma_f32_32x32x16_bf16 v[0:15], v[92:95], v[96:99], v[0:15]
	v_add_u32_e32 v40, v192, v177
	v_add_u32_e32 v42, v193, v177
	ds_read_b64_tr_b16 v[92:93], v40
	ds_read_b64_tr_b16 v[94:95], v42
	s_waitcnt lgkmcnt(12)
	v_mfma_f32_32x32x16_bf16 v[0:15], v[104:107], v[84:87], v[0:15]
	v_add_u32_e32 v40, v194, v177
	v_add_u32_e32 v42, v195, v177
	ds_read_b64_tr_b16 v[104:105], v40
	ds_read_b64_tr_b16 v[106:107], v42
	s_waitcnt lgkmcnt(12)
	v_mfma_f32_32x32x16_bf16 v[0:15], v[108:111], v[80:83], v[0:15]
	v_add_u32_e32 v40, v196, v177
	v_add_u32_e32 v42, v197, v177
	ds_read_b64_tr_b16 v[108:109], v40
	ds_read_b64_tr_b16 v[110:111], v42
	s_waitcnt lgkmcnt(12)
	v_mfma_f32_32x32x16_bf16 v[0:15], v[120:123], v[68:71], v[0:15]
	v_add_u32_e32 v40, v198, v177
	v_add_u32_e32 v42, v199, v177
	ds_read_b64_tr_b16 v[120:121], v40
	ds_read_b64_tr_b16 v[122:123], v42
	s_waitcnt lgkmcnt(12)
	v_mfma_f32_32x32x16_bf16 v[0:15], v[56:59], v[64:67], v[0:15]
	v_add_u32_e32 v40, v200, v177
	v_add_u32_e32 v42, v201, v177
	ds_read_b64_tr_b16 v[56:57], v40
	ds_read_b64_tr_b16 v[58:59], v42
	s_waitcnt lgkmcnt(12)
	v_mfma_f32_32x32x16_bf16 v[0:15], v[60:63], v[52:55], v[0:15]
	v_add_u32_e32 v40, v202, v177
	v_add_u32_e32 v42, v203, v177
	ds_read_b64_tr_b16 v[60:61], v40
	ds_read_b64_tr_b16 v[62:63], v42
	s_waitcnt lgkmcnt(12)
	v_mfma_f32_32x32x16_bf16 v[0:15], v[88:91], v[48:51], v[0:15]
	ds_read_b64_tr_b16 v[88:89], v186 offset:64
	ds_read_b64_tr_b16 v[90:91], v186 offset:4544
	s_waitcnt lgkmcnt(12)
	v_mfma_f32_32x32x16_bf16 v[0:15], v[92:95], v[36:39], v[0:15]
	ds_read_b64_tr_b16 v[92:93], v186 offset:9024
	ds_read_b64_tr_b16 v[94:95], v186 offset:13504
	s_waitcnt lgkmcnt(12)
	v_mfma_f32_32x32x16_bf16 v[0:15], v[104:107], v[32:35], v[0:15]
	ds_read_b64_tr_b16 v[104:105], v186 offset:17984
	ds_read_b64_tr_b16 v[106:107], v186 offset:22464
	s_waitcnt lgkmcnt(12)
	v_mfma_f32_32x32x16_bf16 v[0:15], v[108:111], v[20:23], v[0:15]
	ds_read_b64_tr_b16 v[108:109], v186 offset:26944
	ds_read_b64_tr_b16 v[110:111], v186 offset:31424
	s_waitcnt lgkmcnt(12)
	v_mfma_f32_32x32x16_bf16 v[0:15], v[120:123], v[16:19], v[0:15]
	ds_read_b64_tr_b16 v[120:121], v186 offset:35904
	ds_read_b64_tr_b16 v[122:123], v186 offset:40384
	s_waitcnt lgkmcnt(12)
	v_mfma_f32_32x32x16_bf16 v[0:15], v[56:59], v[28:31], v[0:15]
	ds_read_b64_tr_b16 v[56:57], v186 offset:44864
	ds_read_b64_tr_b16 v[58:59], v186 offset:49344
	s_waitcnt lgkmcnt(12)
	v_mfma_f32_32x32x16_bf16 v[0:15], v[60:63], v[24:27], v[0:15]
	ds_read_b64_tr_b16 v[60:61], v186 offset:53824
	ds_read_b64_tr_b16 v[62:63], v186 offset:58304
	s_nop 11
	v_pk_mul_f32 v[0:1], v[0:1], v[44:45] op_sel_hi:[1,0]
	v_pk_mul_f32 v[2:3], v[2:3], v[44:45] op_sel_hi:[1,0]
	v_pk_mul_f32 v[4:5], v[4:5], v[44:45] op_sel_hi:[1,0]
	v_pk_mul_f32 v[6:7], v[6:7], v[44:45] op_sel_hi:[1,0]
	v_cvt_pk_bf16_f32 v0, v0, v1
	v_cvt_pk_bf16_f32 v1, v2, v3
	v_cvt_pk_bf16_f32 v2, v4, v5
	v_cvt_pk_bf16_f32 v3, v6, v7
	s_nop 1
	v_permlane32_swap_b32_e32 v0, v2
	v_permlane32_swap_b32_e32 v1, v3
	global_store_dwordx4 v[124:125], v[0:3], off
	v_pk_mul_f32 v[8:9], v[8:9], v[44:45] op_sel_hi:[1,0]
	v_pk_mul_f32 v[10:11], v[10:11], v[44:45] op_sel_hi:[1,0]
	v_pk_mul_f32 v[12:13], v[12:13], v[44:45] op_sel_hi:[1,0]
	v_pk_mul_f32 v[14:15], v[14:15], v[44:45] op_sel_hi:[1,0]
	v_cvt_pk_bf16_f32 v4, v8, v9
	v_cvt_pk_bf16_f32 v5, v10, v11
	v_cvt_pk_bf16_f32 v6, v12, v13
	v_cvt_pk_bf16_f32 v7, v14, v15
	s_nop 1
	v_permlane32_swap_b32_e32 v4, v6
	v_permlane32_swap_b32_e32 v5, v7
	global_store_dwordx4 v[124:125], v[4:7], off offset:32
	s_nop 1
	s_waitcnt lgkmcnt(12)
	v_mfma_f32_32x32x16_bf16 v[0:15], v[88:91], v[116:119], 0
	v_add_u32_e32 v40, v187, v204
	ds_read_b64_tr_b16 v[88:89], v186 offset:62784
	ds_read_b64_tr_b16 v[90:91], v40
	s_waitcnt lgkmcnt(12)
	v_mfma_f32_32x32x16_bf16 v[0:15], v[92:95], v[112:115], v[0:15]
	v_add_u32_e32 v40, v188, v204
	v_add_u32_e32 v42, v189, v204
	ds_read_b64_tr_b16 v[92:93], v40
	ds_read_b64_tr_b16 v[94:95], v42
	s_waitcnt lgkmcnt(12)
	v_mfma_f32_32x32x16_bf16 v[0:15], v[104:107], v[100:103], v[0:15]
	v_add_u32_e32 v40, v190, v204
	v_add_u32_e32 v42, v191, v204
	ds_read_b64_tr_b16 v[104:105], v40
	ds_read_b64_tr_b16 v[106:107], v42
	s_waitcnt lgkmcnt(12)
	v_mfma_f32_32x32x16_bf16 v[0:15], v[108:111], v[96:99], v[0:15]
	v_add_u32_e32 v40, v192, v204
	v_add_u32_e32 v42, v193, v204
	ds_read_b64_tr_b16 v[108:109], v40
	ds_read_b64_tr_b16 v[110:111], v42
	s_waitcnt lgkmcnt(12)
	v_mfma_f32_32x32x16_bf16 v[0:15], v[120:123], v[84:87], v[0:15]
	v_add_u32_e32 v40, v194, v204
	v_add_u32_e32 v42, v195, v204
	ds_read_b64_tr_b16 v[120:121], v40
	ds_read_b64_tr_b16 v[122:123], v42
	s_waitcnt lgkmcnt(12)
	v_mfma_f32_32x32x16_bf16 v[0:15], v[56:59], v[80:83], v[0:15]
	v_add_u32_e32 v40, v196, v204
	v_add_u32_e32 v42, v197, v204
	ds_read_b64_tr_b16 v[56:57], v40
	ds_read_b64_tr_b16 v[58:59], v42
	s_waitcnt lgkmcnt(12)
	v_mfma_f32_32x32x16_bf16 v[0:15], v[60:63], v[68:71], v[0:15]
	v_add_u32_e32 v40, v198, v204
	v_add_u32_e32 v42, v199, v204
	ds_read_b64_tr_b16 v[60:61], v40
	ds_read_b64_tr_b16 v[62:63], v42
	s_waitcnt lgkmcnt(12)
	v_mfma_f32_32x32x16_bf16 v[0:15], v[88:91], v[64:67], v[0:15]
	v_add_u32_e32 v40, v200, v204
	v_add_u32_e32 v42, v201, v204
	ds_read_b64_tr_b16 v[88:89], v40
	ds_read_b64_tr_b16 v[90:91], v42
	s_waitcnt lgkmcnt(12)
	v_mfma_f32_32x32x16_bf16 v[0:15], v[92:95], v[52:55], v[0:15]
	v_add_u32_e32 v40, v202, v204
	v_add_u32_e32 v42, v203, v204
	ds_read_b64_tr_b16 v[92:93], v40
	ds_read_b64_tr_b16 v[94:95], v42
	s_waitcnt lgkmcnt(12)
	v_mfma_f32_32x32x16_bf16 v[0:15], v[104:107], v[48:51], v[0:15]
	ds_read_b64_tr_b16 v[104:105], v186 offset:128
	ds_read_b64_tr_b16 v[106:107], v186 offset:4608
	s_waitcnt lgkmcnt(12)
	v_mfma_f32_32x32x16_bf16 v[0:15], v[108:111], v[36:39], v[0:15]
	ds_read_b64_tr_b16 v[108:109], v186 offset:9088
	ds_read_b64_tr_b16 v[110:111], v186 offset:13568
	s_waitcnt lgkmcnt(12)
	v_mfma_f32_32x32x16_bf16 v[0:15], v[120:123], v[32:35], v[0:15]
	ds_read_b64_tr_b16 v[120:121], v186 offset:18048
	ds_read_b64_tr_b16 v[122:123], v186 offset:22528
	s_waitcnt lgkmcnt(12)
	v_mfma_f32_32x32x16_bf16 v[0:15], v[56:59], v[20:23], v[0:15]
	ds_read_b64_tr_b16 v[56:57], v186 offset:27008
	ds_read_b64_tr_b16 v[58:59], v186 offset:31488
	s_waitcnt lgkmcnt(12)
	v_mfma_f32_32x32x16_bf16 v[0:15], v[60:63], v[16:19], v[0:15]
	ds_read_b64_tr_b16 v[60:61], v186 offset:35968
	ds_read_b64_tr_b16 v[62:63], v186 offset:40448
	s_waitcnt lgkmcnt(12)
	v_mfma_f32_32x32x16_bf16 v[0:15], v[88:91], v[28:31], v[0:15]
	ds_read_b64_tr_b16 v[88:89], v186 offset:44928
	ds_read_b64_tr_b16 v[90:91], v186 offset:49408
	s_waitcnt lgkmcnt(12)
	v_mfma_f32_32x32x16_bf16 v[0:15], v[92:95], v[24:27], v[0:15]
	ds_read_b64_tr_b16 v[92:93], v186 offset:53888
	ds_read_b64_tr_b16 v[94:95], v186 offset:58368
	s_nop 11
	v_pk_mul_f32 v[0:1], v[0:1], v[44:45] op_sel_hi:[1,0]
	v_pk_mul_f32 v[2:3], v[2:3], v[44:45] op_sel_hi:[1,0]
	v_pk_mul_f32 v[4:5], v[4:5], v[44:45] op_sel_hi:[1,0]
	v_pk_mul_f32 v[6:7], v[6:7], v[44:45] op_sel_hi:[1,0]
	v_cvt_pk_bf16_f32 v0, v0, v1
	v_cvt_pk_bf16_f32 v1, v2, v3
	v_cvt_pk_bf16_f32 v2, v4, v5
	v_cvt_pk_bf16_f32 v3, v6, v7
	s_nop 1
	v_permlane32_swap_b32_e32 v0, v2
	v_permlane32_swap_b32_e32 v1, v3
	global_store_dwordx4 v[124:125], v[0:3], off offset:64
	v_pk_mul_f32 v[8:9], v[8:9], v[44:45] op_sel_hi:[1,0]
	v_pk_mul_f32 v[10:11], v[10:11], v[44:45] op_sel_hi:[1,0]
	v_pk_mul_f32 v[12:13], v[12:13], v[44:45] op_sel_hi:[1,0]
	v_pk_mul_f32 v[14:15], v[14:15], v[44:45] op_sel_hi:[1,0]
	v_cvt_pk_bf16_f32 v4, v8, v9
	v_cvt_pk_bf16_f32 v5, v10, v11
	v_cvt_pk_bf16_f32 v6, v12, v13
	v_cvt_pk_bf16_f32 v7, v14, v15
	s_nop 1
	v_permlane32_swap_b32_e32 v4, v6
	v_permlane32_swap_b32_e32 v5, v7
	global_store_dwordx4 v[124:125], v[4:7], off offset:96
	s_nop 1
	s_waitcnt lgkmcnt(12)
	v_mfma_f32_32x32x16_bf16 v[0:15], v[104:107], v[116:119], 0
	v_add_u32_e32 v40, v187, v205
	ds_read_b64_tr_b16 v[104:105], v186 offset:62848
	ds_read_b64_tr_b16 v[106:107], v40
	s_waitcnt lgkmcnt(12)
	v_mfma_f32_32x32x16_bf16 v[0:15], v[108:111], v[112:115], v[0:15]
	v_add_u32_e32 v40, v188, v205
	v_add_u32_e32 v42, v189, v205
	ds_read_b64_tr_b16 v[108:109], v40
	ds_read_b64_tr_b16 v[110:111], v42
	s_waitcnt lgkmcnt(12)
	v_mfma_f32_32x32x16_bf16 v[0:15], v[120:123], v[100:103], v[0:15]
	v_add_u32_e32 v40, v190, v205
	v_add_u32_e32 v42, v191, v205
	ds_read_b64_tr_b16 v[120:121], v40
	ds_read_b64_tr_b16 v[122:123], v42
	s_waitcnt lgkmcnt(12)
	v_mfma_f32_32x32x16_bf16 v[0:15], v[56:59], v[96:99], v[0:15]
	v_add_u32_e32 v40, v192, v205
	v_add_u32_e32 v42, v193, v205
	ds_read_b64_tr_b16 v[56:57], v40
	ds_read_b64_tr_b16 v[58:59], v42
	s_waitcnt lgkmcnt(12)
	v_mfma_f32_32x32x16_bf16 v[0:15], v[60:63], v[84:87], v[0:15]
	v_add_u32_e32 v40, v194, v205
	v_add_u32_e32 v42, v195, v205
	ds_read_b64_tr_b16 v[60:61], v40
	ds_read_b64_tr_b16 v[62:63], v42
	s_waitcnt lgkmcnt(12)
	v_mfma_f32_32x32x16_bf16 v[0:15], v[88:91], v[80:83], v[0:15]
	v_add_u32_e32 v40, v196, v205
	v_add_u32_e32 v42, v197, v205
	ds_read_b64_tr_b16 v[88:89], v40
	ds_read_b64_tr_b16 v[90:91], v42
	s_waitcnt lgkmcnt(12)
	v_mfma_f32_32x32x16_bf16 v[0:15], v[92:95], v[68:71], v[0:15]
	v_add_u32_e32 v40, v198, v205
	v_add_u32_e32 v42, v199, v205
	ds_read_b64_tr_b16 v[92:93], v40
	ds_read_b64_tr_b16 v[94:95], v42
	s_waitcnt lgkmcnt(12)
	v_mfma_f32_32x32x16_bf16 v[0:15], v[104:107], v[64:67], v[0:15]
	v_add_u32_e32 v40, v200, v205
	v_add_u32_e32 v42, v201, v205
	ds_read_b64_tr_b16 v[104:105], v40
	ds_read_b64_tr_b16 v[106:107], v42
	s_waitcnt lgkmcnt(12)
	v_mfma_f32_32x32x16_bf16 v[0:15], v[108:111], v[52:55], v[0:15]
	v_add_u32_e32 v40, v202, v205
	v_add_u32_e32 v42, v203, v205
	ds_read_b64_tr_b16 v[108:109], v40
	ds_read_b64_tr_b16 v[110:111], v42
	s_waitcnt lgkmcnt(12)
	v_mfma_f32_32x32x16_bf16 v[0:15], v[120:123], v[48:51], v[0:15]
	ds_read_b64_tr_b16 v[120:121], v186 offset:192
	ds_read_b64_tr_b16 v[122:123], v186 offset:4672
	s_waitcnt lgkmcnt(12)
	v_mfma_f32_32x32x16_bf16 v[0:15], v[56:59], v[36:39], v[0:15]
	ds_read_b64_tr_b16 v[56:57], v186 offset:9152
	ds_read_b64_tr_b16 v[58:59], v186 offset:13632
	s_waitcnt lgkmcnt(12)
	v_mfma_f32_32x32x16_bf16 v[0:15], v[60:63], v[32:35], v[0:15]
	ds_read_b64_tr_b16 v[60:61], v186 offset:18112
	ds_read_b64_tr_b16 v[62:63], v186 offset:22592
	s_waitcnt lgkmcnt(12)
	v_mfma_f32_32x32x16_bf16 v[0:15], v[88:91], v[20:23], v[0:15]
	ds_read_b64_tr_b16 v[88:89], v186 offset:27072
	ds_read_b64_tr_b16 v[90:91], v186 offset:31552
	s_waitcnt lgkmcnt(12)
	v_mfma_f32_32x32x16_bf16 v[0:15], v[92:95], v[16:19], v[0:15]
	ds_read_b64_tr_b16 v[92:93], v186 offset:36032
	ds_read_b64_tr_b16 v[94:95], v186 offset:40512
	s_waitcnt lgkmcnt(12)
	v_mfma_f32_32x32x16_bf16 v[0:15], v[104:107], v[28:31], v[0:15]
	ds_read_b64_tr_b16 v[104:105], v186 offset:44992
	ds_read_b64_tr_b16 v[106:107], v186 offset:49472
	s_waitcnt lgkmcnt(12)
	v_mfma_f32_32x32x16_bf16 v[0:15], v[108:111], v[24:27], v[0:15]
	ds_read_b64_tr_b16 v[108:109], v186 offset:53952
	ds_read_b64_tr_b16 v[110:111], v186 offset:58432
	s_nop 11
	v_pk_mul_f32 v[0:1], v[0:1], v[44:45] op_sel_hi:[1,0]
	v_pk_mul_f32 v[2:3], v[2:3], v[44:45] op_sel_hi:[1,0]
	v_pk_mul_f32 v[4:5], v[4:5], v[44:45] op_sel_hi:[1,0]
	v_pk_mul_f32 v[6:7], v[6:7], v[44:45] op_sel_hi:[1,0]
	v_cvt_pk_bf16_f32 v0, v0, v1
	v_cvt_pk_bf16_f32 v1, v2, v3
	v_cvt_pk_bf16_f32 v2, v4, v5
	v_cvt_pk_bf16_f32 v3, v6, v7
	s_nop 1
	v_permlane32_swap_b32_e32 v0, v2
	v_permlane32_swap_b32_e32 v1, v3
	global_store_dwordx4 v[124:125], v[0:3], off offset:128
	v_pk_mul_f32 v[8:9], v[8:9], v[44:45] op_sel_hi:[1,0]
	v_pk_mul_f32 v[10:11], v[10:11], v[44:45] op_sel_hi:[1,0]
	v_pk_mul_f32 v[12:13], v[12:13], v[44:45] op_sel_hi:[1,0]
	v_pk_mul_f32 v[14:15], v[14:15], v[44:45] op_sel_hi:[1,0]
	v_cvt_pk_bf16_f32 v4, v8, v9
	v_cvt_pk_bf16_f32 v5, v10, v11
	v_cvt_pk_bf16_f32 v6, v12, v13
	v_cvt_pk_bf16_f32 v7, v14, v15
	s_nop 1
	v_permlane32_swap_b32_e32 v4, v6
	v_permlane32_swap_b32_e32 v5, v7
	global_store_dwordx4 v[124:125], v[4:7], off offset:160
	s_nop 1
	s_waitcnt lgkmcnt(12)
	v_mfma_f32_32x32x16_bf16 v[0:15], v[120:123], v[116:119], 0
	v_add_u32_e32 v40, v187, v206
	ds_read_b64_tr_b16 v[120:121], v186 offset:62912
	ds_read_b64_tr_b16 v[122:123], v40
	s_waitcnt lgkmcnt(12)
	v_mfma_f32_32x32x16_bf16 v[0:15], v[56:59], v[112:115], v[0:15]
	v_add_u32_e32 v40, v188, v206
	v_add_u32_e32 v42, v189, v206
	ds_read_b64_tr_b16 v[56:57], v40
	ds_read_b64_tr_b16 v[58:59], v42
	s_waitcnt lgkmcnt(12)
	v_mfma_f32_32x32x16_bf16 v[0:15], v[60:63], v[100:103], v[0:15]
	v_add_u32_e32 v40, v190, v206
	v_add_u32_e32 v42, v191, v206
	ds_read_b64_tr_b16 v[60:61], v40
	ds_read_b64_tr_b16 v[62:63], v42
	s_waitcnt lgkmcnt(12)
	v_mfma_f32_32x32x16_bf16 v[0:15], v[88:91], v[96:99], v[0:15]
	v_add_u32_e32 v40, v192, v206
	v_add_u32_e32 v42, v193, v206
	ds_read_b64_tr_b16 v[88:89], v40
	ds_read_b64_tr_b16 v[90:91], v42
	s_waitcnt lgkmcnt(12)
	v_mfma_f32_32x32x16_bf16 v[0:15], v[92:95], v[84:87], v[0:15]
	v_add_u32_e32 v40, v194, v206
	v_add_u32_e32 v42, v195, v206
	ds_read_b64_tr_b16 v[92:93], v40
	ds_read_b64_tr_b16 v[94:95], v42
	s_waitcnt lgkmcnt(12)
	v_mfma_f32_32x32x16_bf16 v[0:15], v[104:107], v[80:83], v[0:15]
	v_add_u32_e32 v40, v196, v206
	v_add_u32_e32 v42, v197, v206
	ds_read_b64_tr_b16 v[104:105], v40
	ds_read_b64_tr_b16 v[106:107], v42
	s_waitcnt lgkmcnt(12)
	v_mfma_f32_32x32x16_bf16 v[0:15], v[108:111], v[68:71], v[0:15]
	v_add_u32_e32 v40, v198, v206
	v_add_u32_e32 v42, v199, v206
	ds_read_b64_tr_b16 v[108:109], v40
	ds_read_b64_tr_b16 v[110:111], v42
	s_waitcnt lgkmcnt(12)
	v_mfma_f32_32x32x16_bf16 v[0:15], v[120:123], v[64:67], v[0:15]
	v_add_u32_e32 v40, v200, v206
	v_add_u32_e32 v42, v201, v206
	ds_read_b64_tr_b16 v[120:121], v40
	ds_read_b64_tr_b16 v[122:123], v42
	s_waitcnt lgkmcnt(12)
	v_mfma_f32_32x32x16_bf16 v[0:15], v[56:59], v[52:55], v[0:15]
	v_add_u32_e32 v40, v202, v206
	v_add_u32_e32 v42, v203, v206
	ds_read_b64_tr_b16 v[56:57], v40
	ds_read_b64_tr_b16 v[58:59], v42
	s_waitcnt lgkmcnt(12)
	v_mfma_f32_32x32x16_bf16 v[0:15], v[60:63], v[48:51], v[0:15]
	ds_read_b64_tr_b16 v[60:61], v186 offset:256
	ds_read_b64_tr_b16 v[62:63], v186 offset:4736
	s_waitcnt lgkmcnt(12)
	v_mfma_f32_32x32x16_bf16 v[0:15], v[88:91], v[36:39], v[0:15]
	ds_read_b64_tr_b16 v[88:89], v186 offset:9216
	ds_read_b64_tr_b16 v[90:91], v186 offset:13696
	s_waitcnt lgkmcnt(12)
	v_mfma_f32_32x32x16_bf16 v[0:15], v[92:95], v[32:35], v[0:15]
	ds_read_b64_tr_b16 v[92:93], v186 offset:18176
	ds_read_b64_tr_b16 v[94:95], v186 offset:22656
	s_waitcnt lgkmcnt(12)
	v_mfma_f32_32x32x16_bf16 v[0:15], v[104:107], v[20:23], v[0:15]
	ds_read_b64_tr_b16 v[104:105], v186 offset:27136
	ds_read_b64_tr_b16 v[106:107], v186 offset:31616
	s_waitcnt lgkmcnt(12)
	v_mfma_f32_32x32x16_bf16 v[0:15], v[108:111], v[16:19], v[0:15]
	ds_read_b64_tr_b16 v[108:109], v186 offset:36096
	ds_read_b64_tr_b16 v[110:111], v186 offset:40576
	s_waitcnt lgkmcnt(12)
	v_mfma_f32_32x32x16_bf16 v[0:15], v[120:123], v[28:31], v[0:15]
	ds_read_b64_tr_b16 v[120:121], v186 offset:45056
	ds_read_b64_tr_b16 v[122:123], v186 offset:49536
	s_waitcnt lgkmcnt(12)
	v_mfma_f32_32x32x16_bf16 v[0:15], v[56:59], v[24:27], v[0:15]
	ds_read_b64_tr_b16 v[56:57], v186 offset:54016
	ds_read_b64_tr_b16 v[58:59], v186 offset:58496
	s_nop 11
	v_pk_mul_f32 v[0:1], v[0:1], v[44:45] op_sel_hi:[1,0]
	v_pk_mul_f32 v[2:3], v[2:3], v[44:45] op_sel_hi:[1,0]
	v_pk_mul_f32 v[4:5], v[4:5], v[44:45] op_sel_hi:[1,0]
	v_pk_mul_f32 v[6:7], v[6:7], v[44:45] op_sel_hi:[1,0]
	v_cvt_pk_bf16_f32 v0, v0, v1
	v_cvt_pk_bf16_f32 v1, v2, v3
	v_cvt_pk_bf16_f32 v2, v4, v5
	v_cvt_pk_bf16_f32 v3, v6, v7
	s_nop 1
	v_permlane32_swap_b32_e32 v0, v2
	v_permlane32_swap_b32_e32 v1, v3
	global_store_dwordx4 v[124:125], v[0:3], off offset:192
	v_pk_mul_f32 v[8:9], v[8:9], v[44:45] op_sel_hi:[1,0]
	v_pk_mul_f32 v[10:11], v[10:11], v[44:45] op_sel_hi:[1,0]
	v_pk_mul_f32 v[12:13], v[12:13], v[44:45] op_sel_hi:[1,0]
	v_pk_mul_f32 v[14:15], v[14:15], v[44:45] op_sel_hi:[1,0]
	v_cvt_pk_bf16_f32 v4, v8, v9
	v_cvt_pk_bf16_f32 v5, v10, v11
	v_cvt_pk_bf16_f32 v6, v12, v13
	v_cvt_pk_bf16_f32 v7, v14, v15
	s_nop 1
	v_permlane32_swap_b32_e32 v4, v6
	v_permlane32_swap_b32_e32 v5, v7
	global_store_dwordx4 v[124:125], v[4:7], off offset:224
	s_nop 1
	s_waitcnt lgkmcnt(12)
	v_mfma_f32_32x32x16_bf16 v[0:15], v[60:63], v[116:119], 0
	v_add_u32_e32 v40, v187, v207
	ds_read_b64_tr_b16 v[60:61], v186 offset:62976
	ds_read_b64_tr_b16 v[62:63], v40
	s_waitcnt lgkmcnt(12)
	v_mfma_f32_32x32x16_bf16 v[0:15], v[88:91], v[112:115], v[0:15]
	v_add_u32_e32 v40, v188, v207
	v_add_u32_e32 v42, v189, v207
	ds_read_b64_tr_b16 v[88:89], v40
	ds_read_b64_tr_b16 v[90:91], v42
	s_waitcnt lgkmcnt(12)
	v_mfma_f32_32x32x16_bf16 v[0:15], v[92:95], v[100:103], v[0:15]
	v_add_u32_e32 v40, v190, v207
	v_add_u32_e32 v42, v191, v207
	ds_read_b64_tr_b16 v[92:93], v40
	ds_read_b64_tr_b16 v[94:95], v42
	s_waitcnt lgkmcnt(12)
	v_mfma_f32_32x32x16_bf16 v[0:15], v[104:107], v[96:99], v[0:15]
	v_add_u32_e32 v40, v192, v207
	v_add_u32_e32 v42, v193, v207
	ds_read_b64_tr_b16 v[104:105], v40
	ds_read_b64_tr_b16 v[106:107], v42
	s_waitcnt lgkmcnt(12)
	v_mfma_f32_32x32x16_bf16 v[0:15], v[108:111], v[84:87], v[0:15]
	v_add_u32_e32 v40, v194, v207
	v_add_u32_e32 v42, v195, v207
	ds_read_b64_tr_b16 v[108:109], v40
	ds_read_b64_tr_b16 v[110:111], v42
	s_waitcnt lgkmcnt(12)
	v_mfma_f32_32x32x16_bf16 v[0:15], v[120:123], v[80:83], v[0:15]
	v_add_u32_e32 v40, v196, v207
	v_add_u32_e32 v42, v197, v207
	ds_read_b64_tr_b16 v[120:121], v40
	ds_read_b64_tr_b16 v[122:123], v42
	s_waitcnt lgkmcnt(12)
	v_mfma_f32_32x32x16_bf16 v[0:15], v[56:59], v[68:71], v[0:15]
	v_add_u32_e32 v40, v198, v207
	v_add_u32_e32 v42, v199, v207
	ds_read_b64_tr_b16 v[56:57], v40
	ds_read_b64_tr_b16 v[58:59], v42
	s_waitcnt lgkmcnt(12)
	v_mfma_f32_32x32x16_bf16 v[0:15], v[60:63], v[64:67], v[0:15]
	v_add_u32_e32 v40, v200, v207
	v_add_u32_e32 v42, v201, v207
	ds_read_b64_tr_b16 v[60:61], v40
	ds_read_b64_tr_b16 v[62:63], v42
	s_waitcnt lgkmcnt(12)
	v_mfma_f32_32x32x16_bf16 v[0:15], v[88:91], v[52:55], v[0:15]
	v_add_u32_e32 v40, v202, v207
	v_add_u32_e32 v42, v203, v207
	ds_read_b64_tr_b16 v[88:89], v40
	ds_read_b64_tr_b16 v[90:91], v42
	s_waitcnt lgkmcnt(12)
	v_mfma_f32_32x32x16_bf16 v[0:15], v[92:95], v[48:51], v[0:15]
	ds_read_b64_tr_b16 v[92:93], v186 offset:320
	ds_read_b64_tr_b16 v[94:95], v186 offset:4800
	s_waitcnt lgkmcnt(12)
	v_mfma_f32_32x32x16_bf16 v[0:15], v[104:107], v[36:39], v[0:15]
	ds_read_b64_tr_b16 v[104:105], v186 offset:9280
	ds_read_b64_tr_b16 v[106:107], v186 offset:13760
	s_waitcnt lgkmcnt(12)
	v_mfma_f32_32x32x16_bf16 v[0:15], v[108:111], v[32:35], v[0:15]
	ds_read_b64_tr_b16 v[108:109], v186 offset:18240
	ds_read_b64_tr_b16 v[110:111], v186 offset:22720
	s_waitcnt lgkmcnt(12)
	v_mfma_f32_32x32x16_bf16 v[0:15], v[120:123], v[20:23], v[0:15]
	ds_read_b64_tr_b16 v[120:121], v186 offset:27200
	ds_read_b64_tr_b16 v[122:123], v186 offset:31680
	s_waitcnt lgkmcnt(12)
	v_mfma_f32_32x32x16_bf16 v[0:15], v[56:59], v[16:19], v[0:15]
	ds_read_b64_tr_b16 v[56:57], v186 offset:36160
	ds_read_b64_tr_b16 v[58:59], v186 offset:40640
	s_waitcnt lgkmcnt(12)
	v_mfma_f32_32x32x16_bf16 v[0:15], v[60:63], v[28:31], v[0:15]
	ds_read_b64_tr_b16 v[60:61], v186 offset:45120
	ds_read_b64_tr_b16 v[62:63], v186 offset:49600
	s_waitcnt lgkmcnt(12)
	v_mfma_f32_32x32x16_bf16 v[0:15], v[88:91], v[24:27], v[0:15]
	ds_read_b64_tr_b16 v[88:89], v186 offset:54080
	ds_read_b64_tr_b16 v[90:91], v186 offset:58560
	s_nop 11
	v_pk_mul_f32 v[0:1], v[0:1], v[44:45] op_sel_hi:[1,0]
	v_pk_mul_f32 v[2:3], v[2:3], v[44:45] op_sel_hi:[1,0]
	v_pk_mul_f32 v[4:5], v[4:5], v[44:45] op_sel_hi:[1,0]
	v_pk_mul_f32 v[6:7], v[6:7], v[44:45] op_sel_hi:[1,0]
	v_cvt_pk_bf16_f32 v0, v0, v1
	v_cvt_pk_bf16_f32 v1, v2, v3
	v_cvt_pk_bf16_f32 v2, v4, v5
	v_cvt_pk_bf16_f32 v3, v6, v7
	s_nop 1
	v_permlane32_swap_b32_e32 v0, v2
	v_permlane32_swap_b32_e32 v1, v3
	global_store_dwordx4 v[124:125], v[0:3], off offset:256
	v_pk_mul_f32 v[8:9], v[8:9], v[44:45] op_sel_hi:[1,0]
	v_pk_mul_f32 v[10:11], v[10:11], v[44:45] op_sel_hi:[1,0]
	v_pk_mul_f32 v[12:13], v[12:13], v[44:45] op_sel_hi:[1,0]
	v_pk_mul_f32 v[14:15], v[14:15], v[44:45] op_sel_hi:[1,0]
	v_cvt_pk_bf16_f32 v4, v8, v9
	v_cvt_pk_bf16_f32 v5, v10, v11
	v_cvt_pk_bf16_f32 v6, v12, v13
	v_cvt_pk_bf16_f32 v7, v14, v15
	s_nop 1
	v_permlane32_swap_b32_e32 v4, v6
	v_permlane32_swap_b32_e32 v5, v7
	global_store_dwordx4 v[124:125], v[4:7], off offset:288
	s_nop 1
	s_waitcnt lgkmcnt(12)
	v_mfma_f32_32x32x16_bf16 v[0:15], v[92:95], v[116:119], 0
	v_add_u32_e32 v40, v187, v208
	ds_read_b64_tr_b16 v[92:93], v186 offset:63040
	ds_read_b64_tr_b16 v[94:95], v40
	s_waitcnt lgkmcnt(12)
	v_mfma_f32_32x32x16_bf16 v[0:15], v[104:107], v[112:115], v[0:15]
	v_add_u32_e32 v40, v188, v208
	v_add_u32_e32 v42, v189, v208
	ds_read_b64_tr_b16 v[104:105], v40
	ds_read_b64_tr_b16 v[106:107], v42
	s_waitcnt lgkmcnt(12)
	v_mfma_f32_32x32x16_bf16 v[0:15], v[108:111], v[100:103], v[0:15]
	v_add_u32_e32 v40, v190, v208
	v_add_u32_e32 v42, v191, v208
	ds_read_b64_tr_b16 v[108:109], v40
	ds_read_b64_tr_b16 v[110:111], v42
	s_waitcnt lgkmcnt(12)
	v_mfma_f32_32x32x16_bf16 v[0:15], v[120:123], v[96:99], v[0:15]
	v_add_u32_e32 v40, v192, v208
	v_add_u32_e32 v42, v193, v208
	ds_read_b64_tr_b16 v[120:121], v40
	ds_read_b64_tr_b16 v[122:123], v42
	s_waitcnt lgkmcnt(12)
	v_mfma_f32_32x32x16_bf16 v[0:15], v[56:59], v[84:87], v[0:15]
	v_add_u32_e32 v40, v194, v208
	v_add_u32_e32 v42, v195, v208
	ds_read_b64_tr_b16 v[56:57], v40
	ds_read_b64_tr_b16 v[58:59], v42
	s_waitcnt lgkmcnt(12)
	v_mfma_f32_32x32x16_bf16 v[0:15], v[60:63], v[80:83], v[0:15]
	v_add_u32_e32 v40, v196, v208
	v_add_u32_e32 v42, v197, v208
	ds_read_b64_tr_b16 v[60:61], v40
	ds_read_b64_tr_b16 v[62:63], v42
	s_waitcnt lgkmcnt(12)
	v_mfma_f32_32x32x16_bf16 v[0:15], v[88:91], v[68:71], v[0:15]
	v_add_u32_e32 v40, v198, v208
	v_add_u32_e32 v42, v199, v208
	ds_read_b64_tr_b16 v[88:89], v40
	ds_read_b64_tr_b16 v[90:91], v42
	s_waitcnt lgkmcnt(12)
	v_mfma_f32_32x32x16_bf16 v[0:15], v[92:95], v[64:67], v[0:15]
	v_add_u32_e32 v40, v200, v208
	v_add_u32_e32 v42, v201, v208
	ds_read_b64_tr_b16 v[92:93], v40
	ds_read_b64_tr_b16 v[94:95], v42
	s_waitcnt lgkmcnt(12)
	v_mfma_f32_32x32x16_bf16 v[0:15], v[104:107], v[52:55], v[0:15]
	v_add_u32_e32 v40, v202, v208
	v_add_u32_e32 v42, v203, v208
	ds_read_b64_tr_b16 v[104:105], v40
	ds_read_b64_tr_b16 v[106:107], v42
	s_waitcnt lgkmcnt(12)
	v_mfma_f32_32x32x16_bf16 v[0:15], v[108:111], v[48:51], v[0:15]
	ds_read_b64_tr_b16 v[108:109], v186 offset:384
	ds_read_b64_tr_b16 v[110:111], v186 offset:4864
	s_waitcnt lgkmcnt(12)
	v_mfma_f32_32x32x16_bf16 v[0:15], v[120:123], v[36:39], v[0:15]
	ds_read_b64_tr_b16 v[120:121], v186 offset:9344
	ds_read_b64_tr_b16 v[122:123], v186 offset:13824
	s_waitcnt lgkmcnt(12)
	v_mfma_f32_32x32x16_bf16 v[0:15], v[56:59], v[32:35], v[0:15]
	ds_read_b64_tr_b16 v[56:57], v186 offset:18304
	ds_read_b64_tr_b16 v[58:59], v186 offset:22784
	s_waitcnt lgkmcnt(12)
	v_mfma_f32_32x32x16_bf16 v[0:15], v[60:63], v[20:23], v[0:15]
	ds_read_b64_tr_b16 v[60:61], v186 offset:27264
	ds_read_b64_tr_b16 v[62:63], v186 offset:31744
	s_waitcnt lgkmcnt(12)
	v_mfma_f32_32x32x16_bf16 v[0:15], v[88:91], v[16:19], v[0:15]
	ds_read_b64_tr_b16 v[88:89], v186 offset:36224
	ds_read_b64_tr_b16 v[90:91], v186 offset:40704
	s_waitcnt lgkmcnt(12)
	v_mfma_f32_32x32x16_bf16 v[0:15], v[92:95], v[28:31], v[0:15]
	ds_read_b64_tr_b16 v[92:93], v186 offset:45184
	ds_read_b64_tr_b16 v[94:95], v186 offset:49664
	s_waitcnt lgkmcnt(12)
	v_mfma_f32_32x32x16_bf16 v[0:15], v[104:107], v[24:27], v[0:15]
	ds_read_b64_tr_b16 v[104:105], v186 offset:54144
	ds_read_b64_tr_b16 v[106:107], v186 offset:58624
	s_nop 11
	v_pk_mul_f32 v[0:1], v[0:1], v[44:45] op_sel_hi:[1,0]
	v_pk_mul_f32 v[2:3], v[2:3], v[44:45] op_sel_hi:[1,0]
	v_pk_mul_f32 v[4:5], v[4:5], v[44:45] op_sel_hi:[1,0]
	v_pk_mul_f32 v[6:7], v[6:7], v[44:45] op_sel_hi:[1,0]
	v_cvt_pk_bf16_f32 v0, v0, v1
	v_cvt_pk_bf16_f32 v1, v2, v3
	v_cvt_pk_bf16_f32 v2, v4, v5
	v_cvt_pk_bf16_f32 v3, v6, v7
	s_nop 1
	v_permlane32_swap_b32_e32 v0, v2
	v_permlane32_swap_b32_e32 v1, v3
	global_store_dwordx4 v[124:125], v[0:3], off offset:320
	v_pk_mul_f32 v[8:9], v[8:9], v[44:45] op_sel_hi:[1,0]
	v_pk_mul_f32 v[10:11], v[10:11], v[44:45] op_sel_hi:[1,0]
	v_pk_mul_f32 v[12:13], v[12:13], v[44:45] op_sel_hi:[1,0]
	v_pk_mul_f32 v[14:15], v[14:15], v[44:45] op_sel_hi:[1,0]
	v_cvt_pk_bf16_f32 v4, v8, v9
	v_cvt_pk_bf16_f32 v5, v10, v11
	v_cvt_pk_bf16_f32 v6, v12, v13
	v_cvt_pk_bf16_f32 v7, v14, v15
	s_nop 1
	v_permlane32_swap_b32_e32 v4, v6
	v_permlane32_swap_b32_e32 v5, v7
	global_store_dwordx4 v[124:125], v[4:7], off offset:352
	s_nop 1
	s_waitcnt lgkmcnt(12)
	v_mfma_f32_32x32x16_bf16 v[0:15], v[108:111], v[116:119], 0
	v_add_u32_e32 v40, v187, v209
	ds_read_b64_tr_b16 v[108:109], v186 offset:63104
	ds_read_b64_tr_b16 v[110:111], v40
	s_waitcnt lgkmcnt(12)
	v_mfma_f32_32x32x16_bf16 v[0:15], v[120:123], v[112:115], v[0:15]
	v_add_u32_e32 v40, v188, v209
	v_add_u32_e32 v42, v189, v209
	ds_read_b64_tr_b16 v[120:121], v40
	ds_read_b64_tr_b16 v[122:123], v42
	s_waitcnt lgkmcnt(12)
	v_mfma_f32_32x32x16_bf16 v[0:15], v[56:59], v[100:103], v[0:15]
	v_add_u32_e32 v40, v190, v209
	v_add_u32_e32 v42, v191, v209
	ds_read_b64_tr_b16 v[56:57], v40
	ds_read_b64_tr_b16 v[58:59], v42
	s_waitcnt lgkmcnt(12)
	v_mfma_f32_32x32x16_bf16 v[0:15], v[60:63], v[96:99], v[0:15]
	v_add_u32_e32 v40, v192, v209
	v_add_u32_e32 v42, v193, v209
	ds_read_b64_tr_b16 v[60:61], v40
	ds_read_b64_tr_b16 v[62:63], v42
	s_waitcnt lgkmcnt(12)
	v_mfma_f32_32x32x16_bf16 v[0:15], v[88:91], v[84:87], v[0:15]
	v_add_u32_e32 v40, v194, v209
	v_add_u32_e32 v42, v195, v209
	ds_read_b64_tr_b16 v[88:89], v40
	ds_read_b64_tr_b16 v[90:91], v42
	s_waitcnt lgkmcnt(12)
	v_mfma_f32_32x32x16_bf16 v[0:15], v[92:95], v[80:83], v[0:15]
	v_add_u32_e32 v40, v196, v209
	v_add_u32_e32 v42, v197, v209
	ds_read_b64_tr_b16 v[92:93], v40
	ds_read_b64_tr_b16 v[94:95], v42
	s_waitcnt lgkmcnt(12)
	v_mfma_f32_32x32x16_bf16 v[0:15], v[104:107], v[68:71], v[0:15]
	v_add_u32_e32 v40, v198, v209
	v_add_u32_e32 v42, v199, v209
	ds_read_b64_tr_b16 v[104:105], v40
	ds_read_b64_tr_b16 v[106:107], v42
	s_waitcnt lgkmcnt(12)
	v_mfma_f32_32x32x16_bf16 v[0:15], v[108:111], v[64:67], v[0:15]
	v_add_u32_e32 v40, v200, v209
	v_add_u32_e32 v42, v201, v209
	ds_read_b64_tr_b16 v[108:109], v40
	ds_read_b64_tr_b16 v[110:111], v42
	s_waitcnt lgkmcnt(12)
	v_mfma_f32_32x32x16_bf16 v[0:15], v[120:123], v[52:55], v[0:15]
	v_add_u32_e32 v40, v202, v209
	v_add_u32_e32 v42, v203, v209
	ds_read_b64_tr_b16 v[120:121], v40
	ds_read_b64_tr_b16 v[122:123], v42
	s_waitcnt lgkmcnt(12)
	v_mfma_f32_32x32x16_bf16 v[0:15], v[56:59], v[48:51], v[0:15]
	ds_read_b64_tr_b16 v[56:57], v186 offset:448
	ds_read_b64_tr_b16 v[58:59], v186 offset:4928
	s_waitcnt lgkmcnt(12)
	v_mfma_f32_32x32x16_bf16 v[0:15], v[60:63], v[36:39], v[0:15]
	ds_read_b64_tr_b16 v[60:61], v186 offset:9408
	ds_read_b64_tr_b16 v[62:63], v186 offset:13888
	s_waitcnt lgkmcnt(12)
	v_mfma_f32_32x32x16_bf16 v[0:15], v[88:91], v[32:35], v[0:15]
	ds_read_b64_tr_b16 v[88:89], v186 offset:18368
	ds_read_b64_tr_b16 v[90:91], v186 offset:22848
	s_waitcnt lgkmcnt(12)
	v_mfma_f32_32x32x16_bf16 v[0:15], v[92:95], v[20:23], v[0:15]
	ds_read_b64_tr_b16 v[92:93], v186 offset:27328
	ds_read_b64_tr_b16 v[94:95], v186 offset:31808
	s_waitcnt lgkmcnt(12)
	v_mfma_f32_32x32x16_bf16 v[0:15], v[104:107], v[16:19], v[0:15]
	ds_read_b64_tr_b16 v[104:105], v186 offset:36288
	ds_read_b64_tr_b16 v[106:107], v186 offset:40768
	s_waitcnt lgkmcnt(12)
	v_mfma_f32_32x32x16_bf16 v[0:15], v[108:111], v[28:31], v[0:15]
	ds_read_b64_tr_b16 v[108:109], v186 offset:45248
	ds_read_b64_tr_b16 v[110:111], v186 offset:49728
	s_waitcnt lgkmcnt(12)
	v_mfma_f32_32x32x16_bf16 v[0:15], v[120:123], v[24:27], v[0:15]
	ds_read_b64_tr_b16 v[120:121], v186 offset:54208
	ds_read_b64_tr_b16 v[122:123], v186 offset:58688
	s_nop 11
	v_pk_mul_f32 v[0:1], v[0:1], v[44:45] op_sel_hi:[1,0]
	v_pk_mul_f32 v[2:3], v[2:3], v[44:45] op_sel_hi:[1,0]
	v_pk_mul_f32 v[4:5], v[4:5], v[44:45] op_sel_hi:[1,0]
	v_pk_mul_f32 v[6:7], v[6:7], v[44:45] op_sel_hi:[1,0]
	v_cvt_pk_bf16_f32 v0, v0, v1
	v_cvt_pk_bf16_f32 v1, v2, v3
	v_cvt_pk_bf16_f32 v2, v4, v5
	v_cvt_pk_bf16_f32 v3, v6, v7
	s_nop 1
	v_permlane32_swap_b32_e32 v0, v2
	v_permlane32_swap_b32_e32 v1, v3
	global_store_dwordx4 v[124:125], v[0:3], off offset:384
	v_pk_mul_f32 v[8:9], v[8:9], v[44:45] op_sel_hi:[1,0]
	v_pk_mul_f32 v[10:11], v[10:11], v[44:45] op_sel_hi:[1,0]
	v_pk_mul_f32 v[12:13], v[12:13], v[44:45] op_sel_hi:[1,0]
	v_pk_mul_f32 v[14:15], v[14:15], v[44:45] op_sel_hi:[1,0]
	v_cvt_pk_bf16_f32 v4, v8, v9
	v_cvt_pk_bf16_f32 v5, v10, v11
	v_cvt_pk_bf16_f32 v6, v12, v13
	v_cvt_pk_bf16_f32 v7, v14, v15
	s_nop 1
	v_permlane32_swap_b32_e32 v4, v6
	v_permlane32_swap_b32_e32 v5, v7
	global_store_dwordx4 v[124:125], v[4:7], off offset:416
	s_nop 1
	s_waitcnt lgkmcnt(12)
	v_mfma_f32_32x32x16_bf16 v[0:15], v[56:59], v[116:119], 0
	v_add_u32_e32 v40, v187, v210
	ds_read_b64_tr_b16 v[56:57], v186 offset:63168
	ds_read_b64_tr_b16 v[58:59], v40
	s_waitcnt lgkmcnt(12)
	v_mfma_f32_32x32x16_bf16 v[0:15], v[60:63], v[112:115], v[0:15]
	v_add_u32_e32 v40, v188, v210
	v_add_u32_e32 v42, v189, v210
	ds_read_b64_tr_b16 v[60:61], v40
	ds_read_b64_tr_b16 v[62:63], v42
	s_waitcnt lgkmcnt(12)
	v_mfma_f32_32x32x16_bf16 v[0:15], v[88:91], v[100:103], v[0:15]
	v_add_u32_e32 v40, v190, v210
	v_add_u32_e32 v42, v191, v210
	ds_read_b64_tr_b16 v[88:89], v40
	ds_read_b64_tr_b16 v[90:91], v42
	s_waitcnt lgkmcnt(12)
	v_mfma_f32_32x32x16_bf16 v[0:15], v[92:95], v[96:99], v[0:15]
	v_add_u32_e32 v40, v192, v210
	v_add_u32_e32 v42, v193, v210
	ds_read_b64_tr_b16 v[92:93], v40
	ds_read_b64_tr_b16 v[94:95], v42
	s_waitcnt lgkmcnt(12)
	v_mfma_f32_32x32x16_bf16 v[0:15], v[104:107], v[84:87], v[0:15]
	v_add_u32_e32 v40, v194, v210
	v_add_u32_e32 v42, v195, v210
	ds_read_b64_tr_b16 v[104:105], v40
	ds_read_b64_tr_b16 v[106:107], v42
	s_waitcnt lgkmcnt(12)
	v_mfma_f32_32x32x16_bf16 v[0:15], v[108:111], v[80:83], v[0:15]
	v_add_u32_e32 v40, v196, v210
	v_add_u32_e32 v42, v197, v210
	ds_read_b64_tr_b16 v[108:109], v40
	ds_read_b64_tr_b16 v[110:111], v42
	s_waitcnt lgkmcnt(12)
	v_mfma_f32_32x32x16_bf16 v[0:15], v[120:123], v[68:71], v[0:15]
	v_add_u32_e32 v40, v198, v210
	v_add_u32_e32 v42, v199, v210
	ds_read_b64_tr_b16 v[120:121], v40
	ds_read_b64_tr_b16 v[122:123], v42
	s_waitcnt lgkmcnt(12)
	v_mfma_f32_32x32x16_bf16 v[0:15], v[56:59], v[64:67], v[0:15]
	v_add_u32_e32 v40, v200, v210
	v_add_u32_e32 v42, v201, v210
	ds_read_b64_tr_b16 v[56:57], v40
	ds_read_b64_tr_b16 v[58:59], v42
	s_waitcnt lgkmcnt(12)
	v_mfma_f32_32x32x16_bf16 v[0:15], v[60:63], v[52:55], v[0:15]
	v_add_u32_e32 v40, v202, v210
	v_add_u32_e32 v42, v203, v210
	ds_read_b64_tr_b16 v[60:61], v40
	ds_read_b64_tr_b16 v[62:63], v42
	s_waitcnt lgkmcnt(12)
	v_mfma_f32_32x32x16_bf16 v[0:15], v[88:91], v[48:51], v[0:15]
	s_waitcnt lgkmcnt(10)
	v_mfma_f32_32x32x16_bf16 v[0:15], v[92:95], v[36:39], v[0:15]
	s_waitcnt lgkmcnt(8)
	v_mfma_f32_32x32x16_bf16 v[0:15], v[104:107], v[32:35], v[0:15]
	s_waitcnt lgkmcnt(6)
	v_mfma_f32_32x32x16_bf16 v[0:15], v[108:111], v[20:23], v[0:15]
	s_waitcnt lgkmcnt(4)
	v_mfma_f32_32x32x16_bf16 v[0:15], v[120:123], v[16:19], v[0:15]
	s_waitcnt lgkmcnt(2)
	v_mfma_f32_32x32x16_bf16 v[0:15], v[56:59], v[28:31], v[0:15]
	s_waitcnt lgkmcnt(0)
	v_mfma_f32_32x32x16_bf16 v[0:15], v[60:63], v[24:27], v[0:15]
	s_nop 11
	v_pk_mul_f32 v[0:1], v[0:1], v[44:45] op_sel_hi:[1,0]
	v_pk_mul_f32 v[2:3], v[2:3], v[44:45] op_sel_hi:[1,0]
	v_pk_mul_f32 v[4:5], v[4:5], v[44:45] op_sel_hi:[1,0]
	v_pk_mul_f32 v[6:7], v[6:7], v[44:45] op_sel_hi:[1,0]
	v_cvt_pk_bf16_f32 v0, v0, v1
	v_cvt_pk_bf16_f32 v1, v2, v3
	v_cvt_pk_bf16_f32 v2, v4, v5
	v_cvt_pk_bf16_f32 v3, v6, v7
	s_nop 1
	v_permlane32_swap_b32_e32 v0, v2
	v_permlane32_swap_b32_e32 v1, v3
	global_store_dwordx4 v[124:125], v[0:3], off offset:448
	v_pk_mul_f32 v[8:9], v[8:9], v[44:45] op_sel_hi:[1,0]
	v_pk_mul_f32 v[10:11], v[10:11], v[44:45] op_sel_hi:[1,0]
	v_pk_mul_f32 v[12:13], v[12:13], v[44:45] op_sel_hi:[1,0]
	v_pk_mul_f32 v[14:15], v[14:15], v[44:45] op_sel_hi:[1,0]
	v_cvt_pk_bf16_f32 v4, v8, v9
	v_cvt_pk_bf16_f32 v5, v10, v11
	v_cvt_pk_bf16_f32 v6, v12, v13
	v_cvt_pk_bf16_f32 v7, v14, v15
	s_nop 1
	v_permlane32_swap_b32_e32 v4, v6
	v_permlane32_swap_b32_e32 v5, v7
	global_store_dwordx4 v[124:125], v[4:7], off offset:480
	s_nop 1
	s_barrier
	s_branch .LBB0_751
